# dn_prep forward substitution: result rows 0..47 stored as soon as final, interleaved with the updates of the rows below (role selected by exec mask), store tail cut to 16 rows
# baseline (speedup 1.0000x reference)
.LBB0_809:
	v_readlane_b32 s6, v253, 34
	s_waitcnt lgkmcnt(0)
	s_barrier
	v_mov_b32_e32 v5, s6
	ds_read_b128 v[146:149], v5 offset:18688
	ds_read_b128 v[150:153], v5 offset:18944
	ds_read_b128 v[178:181], v5 offset:19200
	ds_read_b128 v[182:185], v5 offset:19456
	ds_read_b128 v[186:189], v5 offset:19712
	ds_read_b128 v[190:193], v5 offset:19728
	ds_read_b128 v[194:197], v5 offset:19968
	ds_read_b128 v[198:201], v5 offset:19984
	ds_read_b128 v[202:205], v5 offset:20224
	ds_read_b128 v[206:209], v5 offset:20240
	ds_read_b128 v[214:217], v5 offset:20480
	ds_read_b128 v[228:231], v5 offset:20496
	s_waitcnt lgkmcnt(11)
	v_fma_f32 v0, -v60, v146, v61
	v_fma_f32 v0, -v61, v147, v0
	v_fma_f32 v0, -v82, v148, v0
	v_fma_f32 v0, -v83, v149, v0
	ds_read_b128 v[232:235], v5 offset:20736
	s_waitcnt lgkmcnt(11)
	v_fma_f32 v1, -v60, v150, v82
	v_fma_f32 v1, -v151, v0, v1
	v_fma_f32 v1, -v82, v152, v1
	v_fma_f32 v1, -v83, v153, v1
	ds_read_b128 v[244:247], v5 offset:20752
	s_waitcnt lgkmcnt(11)
	v_fma_f32 v2, -v60, v178, v83
	v_fma_f32 v2, -v179, v0, v2
	v_fma_f32 v2, -v180, v1, v2
	v_fma_f32 v2, -v83, v181, v2
	ds_read_b128 v[146:149], v5 offset:20768
	s_waitcnt lgkmcnt(11)
	v_fma_f32 v3, -v60, v182, v86
	v_fma_f32 v3, -v183, v0, v3
	v_fma_f32 v3, -v184, v1, v3
	v_fma_f32 v3, -v185, v2, v3
	ds_read_b128 v[150:153], v5 offset:20992
	s_waitcnt lgkmcnt(11)
	v_fma_f32 v4, -v60, v186, v87
	v_fma_f32 v4, -v187, v0, v4
	v_fma_f32 v4, -v188, v1, v4
	v_fma_f32 v4, -v189, v2, v4
	ds_read_b128 v[178:181], v5 offset:21008
	s_waitcnt lgkmcnt(11)
	v_fma_f32 v4, -v190, v3, v4
	v_fma_f32 v4, -v87, v191, v4
	v_fma_f32 v4, -v80, v192, v4
	v_fma_f32 v4, -v81, v193, v4
	ds_read_b128 v[182:185], v5 offset:21024
	s_waitcnt lgkmcnt(11)
	v_fma_f32 v6, -v60, v194, v80
	v_fma_f32 v6, -v0, v195, v6
	v_fma_f32 v6, -v196, v1, v6
	v_fma_f32 v10, -v197, v2, v6
	ds_read_b128 v[186:189], v5 offset:21248
	s_waitcnt lgkmcnt(11)
	v_fma_f32 v6, -v198, v3, v10
	v_fma_f32 v6, -v199, v4, v6
	v_fma_f32 v6, -v80, v200, v6
	v_fma_f32 v6, -v81, v201, v6
	ds_read_b128 v[190:193], v5 offset:21264
	s_waitcnt lgkmcnt(11)
	v_fma_f32 v7, -v60, v202, v81
	v_fma_f32 v7, -v0, v203, v7
	v_fma_f32 v7, -v204, v1, v7
	v_fma_f32 v7, -v205, v2, v7
	ds_read_b128 v[194:197], v5 offset:21280
	s_waitcnt lgkmcnt(11)
	v_fma_f32 v7, -v206, v3, v7
	v_fma_f32 v7, -v207, v4, v7
	v_fma_f32 v7, -v208, v6, v7
	v_fma_f32 v7, -v81, v209, v7
	ds_read_b128 v[198:201], v5 offset:21504
	s_waitcnt lgkmcnt(11)
	v_fma_f32 v8, -v60, v214, v72
	v_fma_f32 v8, -v0, v215, v8
	v_fma_f32 v8, -v1, v216, v8
	v_fma_f32 v12, -v217, v2, v8
	ds_read_b128 v[202:205], v5 offset:21520
	s_waitcnt lgkmcnt(11)
	v_fma_f32 v8, -v228, v3, v12
	v_fma_f32 v8, -v229, v4, v8
	v_fma_f32 v8, -v230, v6, v8
	v_fma_f32 v8, -v231, v7, v8
	ds_read_b128 v[206:209], v5 offset:21536
	s_waitcnt lgkmcnt(11)
	v_fma_f32 v9, -v60, v232, v73
	v_fma_f32 v9, -v0, v233, v9
	v_fma_f32 v9, -v1, v234, v9
	v_fma_f32 v9, -v235, v2, v9
	ds_read_b128 v[214:217], v5 offset:21760
	s_waitcnt lgkmcnt(11)
	v_fma_f32 v9, -v244, v3, v9
	v_fma_f32 v9, -v245, v4, v9
	v_fma_f32 v9, -v246, v6, v9
	v_fma_f32 v9, -v247, v7, v9
	ds_read_b128 v[228:231], v5 offset:21776
	s_waitcnt lgkmcnt(11)
	v_fma_f32 v9, -v146, v8, v9
	v_fma_f32 v9, -v73, v147, v9
	v_fma_f32 v9, -v54, v148, v9
	v_fma_f32 v9, -v55, v149, v9
	ds_read_b128 v[232:235], v5 offset:21792
	s_waitcnt lgkmcnt(11)
	v_fma_f32 v10, -v60, v150, v54
	v_fma_f32 v10, -v0, v151, v10
	v_fma_f32 v10, -v1, v152, v10
	v_fma_f32 v14, -v2, v153, v10
	ds_read_b128 v[244:247], v5 offset:21808
	s_waitcnt lgkmcnt(11)
	v_fma_f32 v10, -v3, v178, v14
	v_fma_f32 v10, -v179, v4, v10
	v_fma_f32 v10, -v180, v6, v10
	v_fma_f32 v14, -v181, v7, v10
	ds_read_b128 v[146:149], v5 offset:22016
	s_waitcnt lgkmcnt(11)
	v_fma_f32 v10, -v182, v8, v14
	v_fma_f32 v10, -v183, v9, v10
	v_fma_f32 v10, -v54, v184, v10
	v_fma_f32 v10, -v55, v185, v10
	ds_read_b128 v[150:153], v5 offset:22032
	s_waitcnt lgkmcnt(11)
	v_fma_f32 v11, -v60, v186, v55
	v_fma_f32 v11, -v0, v187, v11
	v_fma_f32 v11, -v1, v188, v11
	v_fma_f32 v11, -v2, v189, v11
	ds_read_b128 v[178:181], v5 offset:22048
	s_waitcnt lgkmcnt(11)
	v_fma_f32 v11, -v3, v190, v11
	v_fma_f32 v11, -v191, v4, v11
	v_fma_f32 v11, -v192, v6, v11
	v_fma_f32 v11, -v193, v7, v11
	ds_read_b128 v[182:185], v5 offset:22064
	s_waitcnt lgkmcnt(11)
	v_fma_f32 v11, -v194, v8, v11
	v_fma_f32 v11, -v195, v9, v11
	v_fma_f32 v11, -v196, v10, v11
	v_fma_f32 v11, -v55, v197, v11
	ds_read_b128 v[186:189], v5 offset:22272
	s_waitcnt lgkmcnt(11)
	v_fma_f32 v12, -v60, v198, v52
	v_fma_f32 v12, -v0, v199, v12
	v_fma_f32 v12, -v1, v200, v12
	v_fma_f32 v16, -v2, v201, v12
	ds_read_b128 v[190:193], v5 offset:22288
	s_waitcnt lgkmcnt(11)
	v_fma_f32 v12, -v3, v202, v16
	v_fma_f32 v12, -v4, v203, v12
	v_fma_f32 v12, -v204, v6, v12
	v_fma_f32 v16, -v205, v7, v12
	ds_read_b128 v[194:197], v5 offset:22304
	s_waitcnt lgkmcnt(11)
	v_fma_f32 v12, -v206, v8, v16
	v_fma_f32 v12, -v207, v9, v12
	v_fma_f32 v12, -v208, v10, v12
	v_fma_f32 v12, -v209, v11, v12
	ds_read_b128 v[198:201], v5 offset:22320
	s_waitcnt lgkmcnt(11)
	v_fma_f32 v13, -v60, v214, v53
	v_fma_f32 v13, -v0, v215, v13
	v_fma_f32 v13, -v1, v216, v13
	v_fma_f32 v13, -v2, v217, v13
	ds_read_b128 v[202:205], v5 offset:22528
	s_waitcnt lgkmcnt(11)
	v_fma_f32 v13, -v3, v228, v13
	v_fma_f32 v13, -v4, v229, v13
	v_fma_f32 v13, -v6, v230, v13
	v_fma_f32 v13, -v231, v7, v13
	ds_read_b128 v[206:209], v5 offset:22544
	s_waitcnt lgkmcnt(11)
	v_fma_f32 v13, -v232, v8, v13
	v_fma_f32 v13, -v233, v9, v13
	v_fma_f32 v13, -v234, v10, v13
	v_fma_f32 v13, -v235, v11, v13
	ds_read_b128 v[214:217], v5 offset:22560
	s_waitcnt lgkmcnt(11)
	v_fma_f32 v13, -v244, v12, v13
	v_fma_f32 v13, -v53, v245, v13
	v_fma_f32 v13, -v50, v246, v13
	v_fma_f32 v13, -v51, v247, v13
	ds_read_b128 v[228:231], v5 offset:22576
	s_waitcnt lgkmcnt(11)
	v_fma_f32 v14, -v60, v146, v50
	v_fma_f32 v14, -v0, v147, v14
	v_fma_f32 v14, -v1, v148, v14
	v_fma_f32 v18, -v2, v149, v14
	ds_read_b128 v[232:235], v5 offset:22800
	s_waitcnt lgkmcnt(11)
	v_fma_f32 v14, -v3, v150, v18
	v_fma_f32 v14, -v4, v151, v14
	v_fma_f32 v14, -v6, v152, v14
	v_fma_f32 v18, -v7, v153, v14
	ds_read_b128 v[244:247], v5 offset:22784
	s_waitcnt lgkmcnt(11)
	v_fma_f32 v14, -v8, v178, v18
	v_fma_f32 v14, -v179, v9, v14
	v_fma_f32 v14, -v180, v10, v14
	v_fma_f32 v18, -v181, v11, v14
	ds_read_b128 v[146:149], v5 offset:22832
	s_waitcnt lgkmcnt(11)
	v_fma_f32 v14, -v182, v12, v18
	v_fma_f32 v14, -v183, v13, v14
	v_fma_f32 v14, -v50, v184, v14
	v_fma_f32 v14, -v51, v185, v14
	ds_read_b128 v[150:153], v5 offset:22816
	s_waitcnt lgkmcnt(11)
	v_fma_f32 v15, -v60, v186, v51
	v_fma_f32 v15, -v0, v187, v15
	v_fma_f32 v15, -v1, v188, v15
	v_fma_f32 v15, -v2, v189, v15
	ds_read_b128 v[178:181], v5 offset:23040
	s_waitcnt lgkmcnt(11)
	v_fma_f32 v15, -v3, v190, v15
	v_fma_f32 v15, -v4, v191, v15
	v_fma_f32 v15, -v6, v192, v15
	v_fma_f32 v15, -v7, v193, v15
	ds_read_b128 v[182:185], v5 offset:23056
	s_waitcnt lgkmcnt(11)
	v_fma_f32 v15, -v8, v194, v15
	v_fma_f32 v15, -v9, v195, v15
	v_fma_f32 v15, -v196, v10, v15
	v_fma_f32 v15, -v197, v11, v15
	ds_read_b128 v[186:189], v5 offset:23072
	s_waitcnt lgkmcnt(11)
	v_fma_f32 v15, -v198, v12, v15
	v_fma_f32 v15, -v199, v13, v15
	v_fma_f32 v15, -v200, v14, v15
	v_fma_f32 v15, -v51, v201, v15
	ds_read_b128 v[190:193], v5 offset:23088
	v_lshl_add_u64 v[154:155], v[66:67], 2, s[2:3]
	s_mov_b64 s[100:101], 0x4000
	v_lshl_add_u64 v[210:211], v[68:69], 0, s[100:101]
	v_readlane_b32 s100, v253, 32
	v_readlane_b32 s101, v253, 33
	s_nop 3
	s_mov_b64 exec, s[100:101]
	v_cvt_pk_bf16_f32 v238, -v60, s0
	global_store_short v[210:211], v238, off
	s_not_b64 exec, s[100:101]
	global_store_dword v[154:155], v60, off
	s_mov_b64 exec, -1
	s_waitcnt lgkmcnt(11)
	v_fma_f32 v16, v60, v202, 0
	v_fma_f32 v17, v0, v203, 0
	v_fmac_f32_e32 v16, v1, v204
	v_fmac_f32_e32 v17, v2, v205
	ds_read_b128 v[194:197], v5 offset:23312
	s_waitcnt lgkmcnt(11)
	v_fmac_f32_e32 v16, v3, v206
	v_fmac_f32_e32 v17, v4, v207
	v_fmac_f32_e32 v16, v6, v208
	v_fmac_f32_e32 v17, v7, v209
	ds_read_b128 v[198:201], v5 offset:23296
	s_waitcnt lgkmcnt(11)
	v_fmac_f32_e32 v16, v8, v214
	v_fmac_f32_e32 v17, v9, v215
	v_fmac_f32_e32 v16, v10, v216
	v_fmac_f32_e32 v17, v217, v11
	ds_read_b128 v[202:205], v5 offset:23344
	s_waitcnt lgkmcnt(11)
	v_fmac_f32_e32 v16, v228, v12
	v_fmac_f32_e32 v17, v229, v13
	v_fmac_f32_e32 v16, v230, v14
	v_fmac_f32_e32 v17, v231, v15
	ds_read_b128 v[206:209], v5 offset:23328
	v_add_f32_e32 v16, v16, v17
	s_waitcnt lgkmcnt(10)
	v_fma_f32 v17, v60, v244, 0
	v_fma_f32 v22, v0, v245, 0
	v_fmac_f32_e32 v17, v1, v246
	v_fmac_f32_e32 v22, v2, v247
	ds_read_b128 v[214:217], v5 offset:23552
	v_fmac_f32_e32 v17, v3, v232
	v_fmac_f32_e32 v22, v4, v233
	v_fmac_f32_e32 v17, v6, v234
	v_fmac_f32_e32 v22, v7, v235
	ds_read_b128 v[228:231], v5 offset:23568
	s_waitcnt lgkmcnt(10)
	v_fmac_f32_e32 v17, v8, v150
	v_fmac_f32_e32 v22, v9, v151
	v_fmac_f32_e32 v17, v10, v152
	v_fmac_f32_e32 v22, v11, v153
	ds_read_b128 v[244:247], v5 offset:23584
	v_fmac_f32_e32 v17, v146, v12
	v_fmac_f32_e32 v22, v147, v13
	v_fmac_f32_e32 v17, v148, v14
	v_fmac_f32_e32 v22, v149, v15
	ds_read_b128 v[232:235], v5 offset:23600
	v_add_f32_e32 v17, v17, v22
	v_sub_f32_e32 v16, v48, v16
	v_sub_f32_e32 v17, v49, v17
	s_mov_b64 exec, s[100:101]
	v_cvt_pk_bf16_f32 v238, -v0, s0
	global_store_short v[210:211], v238, off offset:128
	s_not_b64 exec, s[100:101]
	global_store_dword v[154:155], v0, off offset:256
	s_mov_b64 exec, -1
	s_waitcnt lgkmcnt(11)
	v_fma_f32 v18, v60, v178, 0
	v_fma_f32 v19, v0, v179, 0
	v_fmac_f32_e32 v18, v1, v180
	v_fmac_f32_e32 v19, v2, v181
	ds_read_b128 v[150:153], v5 offset:23824
	s_waitcnt lgkmcnt(11)
	v_fmac_f32_e32 v18, v3, v182
	v_fmac_f32_e32 v19, v4, v183
	v_fmac_f32_e32 v18, v6, v184
	v_fmac_f32_e32 v19, v7, v185
	ds_read_b128 v[146:149], v5 offset:23808
	s_waitcnt lgkmcnt(11)
	v_fmac_f32_e32 v18, v8, v186
	v_fmac_f32_e32 v19, v9, v187
	v_fmac_f32_e32 v18, v10, v188
	v_fmac_f32_e32 v19, v11, v189
	ds_read_b128 v[178:181], v5 offset:23856
	s_waitcnt lgkmcnt(11)
	v_fmac_f32_e32 v18, v12, v190
	v_fmac_f32_e32 v19, v13, v191
	v_fmac_f32_e32 v18, v192, v14
	v_fmac_f32_e32 v19, v193, v15
	ds_read_b128 v[182:185], v5 offset:23840
	v_add_f32_e32 v18, v18, v19
	s_waitcnt lgkmcnt(10)
	v_fma_f32 v19, v60, v198, 0
	v_fma_f32 v24, v0, v199, 0
	v_fmac_f32_e32 v19, v1, v200
	v_fmac_f32_e32 v24, v2, v201
	ds_read_b128 v[186:189], v5 offset:24064
	v_fmac_f32_e32 v19, v3, v194
	v_fmac_f32_e32 v24, v4, v195
	v_fmac_f32_e32 v19, v6, v196
	v_fmac_f32_e32 v24, v7, v197
	ds_read_b128 v[190:193], v5 offset:24080
	s_waitcnt lgkmcnt(10)
	v_fmac_f32_e32 v19, v8, v206
	v_fmac_f32_e32 v24, v9, v207
	v_fmac_f32_e32 v19, v10, v208
	v_fmac_f32_e32 v24, v11, v209
	ds_read_b128 v[198:201], v5 offset:24096
	v_fmac_f32_e32 v19, v12, v202
	v_fmac_f32_e32 v24, v13, v203
	v_fmac_f32_e32 v19, v204, v14
	v_fmac_f32_e32 v24, v205, v15
	ds_read_b128 v[194:197], v5 offset:24112
	v_add_f32_e32 v19, v19, v24
	v_sub_f32_e32 v18, v44, v18
	v_sub_f32_e32 v19, v45, v19
	s_mov_b64 exec, s[100:101]
	v_cvt_pk_bf16_f32 v238, -v1, s0
	global_store_short v[210:211], v238, off offset:256
	s_not_b64 exec, s[100:101]
	global_store_dword v[154:155], v1, off offset:512
	s_mov_b64 exec, -1
	s_waitcnt lgkmcnt(11)
	v_fma_f32 v20, v60, v214, 0
	v_fma_f32 v21, v0, v215, 0
	v_fmac_f32_e32 v20, v1, v216
	v_fmac_f32_e32 v21, v2, v217
	ds_read_b128 v[206:209], v5 offset:24336
	s_waitcnt lgkmcnt(11)
	v_fmac_f32_e32 v20, v3, v228
	v_fmac_f32_e32 v21, v4, v229
	v_fmac_f32_e32 v20, v6, v230
	v_fmac_f32_e32 v21, v7, v231
	ds_read_b128 v[202:205], v5 offset:24320
	s_waitcnt lgkmcnt(11)
	v_fmac_f32_e32 v20, v8, v244
	v_fmac_f32_e32 v21, v9, v245
	v_fmac_f32_e32 v20, v10, v246
	v_fmac_f32_e32 v21, v11, v247
	ds_read_b128 v[214:217], v5 offset:24368
	s_waitcnt lgkmcnt(11)
	v_fmac_f32_e32 v20, v12, v232
	v_fmac_f32_e32 v21, v13, v233
	v_fmac_f32_e32 v20, v14, v234
	v_fmac_f32_e32 v21, v15, v235
	ds_read_b128 v[228:231], v5 offset:24352
	v_add_f32_e32 v20, v20, v21
	s_waitcnt lgkmcnt(10)
	v_fma_f32 v21, v60, v146, 0
	v_fma_f32 v26, v0, v147, 0
	v_fmac_f32_e32 v21, v1, v148
	v_fmac_f32_e32 v26, v2, v149
	ds_read_b128 v[244:247], v5 offset:24576
	v_fmac_f32_e32 v21, v3, v150
	v_fmac_f32_e32 v26, v4, v151
	v_fmac_f32_e32 v21, v6, v152
	v_fmac_f32_e32 v26, v7, v153
	ds_read_b128 v[232:235], v5 offset:24592
	s_waitcnt lgkmcnt(10)
	v_fmac_f32_e32 v21, v8, v182
	v_fmac_f32_e32 v26, v9, v183
	v_fmac_f32_e32 v21, v10, v184
	v_fmac_f32_e32 v26, v11, v185
	ds_read_b128 v[146:149], v5 offset:24608
	v_fmac_f32_e32 v21, v12, v178
	v_fmac_f32_e32 v26, v13, v179
	v_fmac_f32_e32 v21, v14, v180
	v_fmac_f32_e32 v26, v15, v181
	ds_read_b128 v[150:153], v5 offset:24624
	v_add_f32_e32 v21, v21, v26
	v_sub_f32_e32 v20, v46, v20
	v_sub_f32_e32 v21, v47, v21
	s_mov_b64 exec, s[100:101]
	v_cvt_pk_bf16_f32 v238, -v2, s0
	global_store_short v[210:211], v238, off offset:384
	s_not_b64 exec, s[100:101]
	global_store_dword v[154:155], v2, off offset:768
	s_mov_b64 exec, -1
	s_waitcnt lgkmcnt(11)
	v_fma_f32 v22, v60, v186, 0
	v_fma_f32 v23, v0, v187, 0
	v_fmac_f32_e32 v22, v1, v188
	v_fmac_f32_e32 v23, v2, v189
	ds_read_b128 v[182:185], v5 offset:24848
	s_waitcnt lgkmcnt(11)
	v_fmac_f32_e32 v22, v3, v190
	v_fmac_f32_e32 v23, v4, v191
	v_fmac_f32_e32 v22, v6, v192
	v_fmac_f32_e32 v23, v7, v193
	ds_read_b128 v[178:181], v5 offset:24832
	s_waitcnt lgkmcnt(11)
	v_fmac_f32_e32 v22, v8, v198
	v_fmac_f32_e32 v23, v9, v199
	v_fmac_f32_e32 v22, v10, v200
	v_fmac_f32_e32 v23, v11, v201
	ds_read_b128 v[186:189], v5 offset:24880
	s_waitcnt lgkmcnt(11)
	v_fmac_f32_e32 v22, v12, v194
	v_fmac_f32_e32 v23, v13, v195
	v_fmac_f32_e32 v22, v14, v196
	v_fmac_f32_e32 v23, v15, v197
	ds_read_b128 v[190:193], v5 offset:24864
	v_add_f32_e32 v22, v22, v23
	s_waitcnt lgkmcnt(10)
	v_fma_f32 v23, v60, v202, 0
	v_fma_f32 v28, v0, v203, 0
	v_fmac_f32_e32 v23, v1, v204
	v_fmac_f32_e32 v28, v2, v205
	ds_read_b128 v[198:201], v5 offset:25088
	v_fmac_f32_e32 v23, v3, v206
	v_fmac_f32_e32 v28, v4, v207
	v_fmac_f32_e32 v23, v6, v208
	v_fmac_f32_e32 v28, v7, v209
	ds_read_b128 v[194:197], v5 offset:25104
	s_waitcnt lgkmcnt(10)
	v_fmac_f32_e32 v23, v8, v228
	v_fmac_f32_e32 v28, v9, v229
	v_fmac_f32_e32 v23, v10, v230
	v_fmac_f32_e32 v28, v11, v231
	ds_read_b128 v[202:205], v5 offset:25120
	v_fmac_f32_e32 v23, v12, v214
	v_fmac_f32_e32 v28, v13, v215
	v_fmac_f32_e32 v23, v14, v216
	v_fmac_f32_e32 v28, v15, v217
	ds_read_b128 v[206:209], v5 offset:25136
	v_add_f32_e32 v23, v23, v28
	v_sub_f32_e32 v22, v42, v22
	v_sub_f32_e32 v23, v43, v23
	s_mov_b64 exec, s[100:101]
	v_cvt_pk_bf16_f32 v238, -v3, s0
	global_store_short v[210:211], v238, off offset:512
	s_not_b64 exec, s[100:101]
	global_store_dword v[154:155], v3, off offset:1024
	s_mov_b64 exec, -1
	s_waitcnt lgkmcnt(11)
	v_fma_f32 v24, v60, v244, 0
	v_fma_f32 v25, v0, v245, 0
	v_fmac_f32_e32 v24, v1, v246
	v_fmac_f32_e32 v25, v2, v247
	ds_read_b128 v[228:231], v5 offset:25360
	s_waitcnt lgkmcnt(11)
	v_fmac_f32_e32 v24, v3, v232
	v_fmac_f32_e32 v25, v4, v233
	v_fmac_f32_e32 v24, v6, v234
	v_fmac_f32_e32 v25, v7, v235
	ds_read_b128 v[214:217], v5 offset:25344
	s_waitcnt lgkmcnt(11)
	v_fmac_f32_e32 v24, v8, v146
	v_fmac_f32_e32 v25, v9, v147
	v_fmac_f32_e32 v24, v10, v148
	v_fmac_f32_e32 v25, v11, v149
	ds_read_b128 v[244:247], v5 offset:25392
	s_waitcnt lgkmcnt(11)
	v_fmac_f32_e32 v24, v12, v150
	v_fmac_f32_e32 v25, v13, v151
	v_fmac_f32_e32 v24, v14, v152
	v_fmac_f32_e32 v25, v15, v153
	ds_read_b128 v[232:235], v5 offset:25376
	v_add_f32_e32 v24, v24, v25
	v_sub_f32_e32 v24, v40, v24
	s_waitcnt lgkmcnt(10)
	v_fma_f32 v25, v60, v178, 0
	v_fma_f32 v40, v0, v179, 0
	v_fmac_f32_e32 v25, v1, v180
	v_fmac_f32_e32 v40, v2, v181
	ds_read_b128 v[146:149], v5 offset:25600
	v_fmac_f32_e32 v25, v3, v182
	v_fmac_f32_e32 v40, v4, v183
	v_fmac_f32_e32 v25, v6, v184
	v_fmac_f32_e32 v40, v7, v185
	ds_read_b128 v[150:153], v5 offset:25616
	s_waitcnt lgkmcnt(10)
	v_fmac_f32_e32 v25, v8, v190
	v_fmac_f32_e32 v40, v9, v191
	v_fmac_f32_e32 v25, v10, v192
	v_fmac_f32_e32 v40, v11, v193
	ds_read_b128 v[178:181], v5 offset:25632
	v_fmac_f32_e32 v25, v12, v186
	v_fmac_f32_e32 v40, v13, v187
	v_fmac_f32_e32 v25, v14, v188
	v_fmac_f32_e32 v40, v15, v189
	ds_read_b128 v[182:185], v5 offset:25648
	v_add_f32_e32 v25, v25, v40
	v_sub_f32_e32 v25, v41, v25
	s_mov_b64 exec, s[100:101]
	v_cvt_pk_bf16_f32 v238, -v4, s0
	global_store_short v[210:211], v238, off offset:640
	s_not_b64 exec, s[100:101]
	global_store_dword v[154:155], v4, off offset:1280
	s_mov_b64 exec, -1
	s_waitcnt lgkmcnt(11)
	v_fma_f32 v26, v60, v198, 0
	v_fma_f32 v27, v0, v199, 0
	v_fmac_f32_e32 v26, v1, v200
	v_fmac_f32_e32 v27, v2, v201
	ds_read_b128 v[190:193], v5 offset:25872
	s_waitcnt lgkmcnt(11)
	v_fmac_f32_e32 v26, v3, v194
	v_fmac_f32_e32 v27, v4, v195
	v_fmac_f32_e32 v26, v6, v196
	v_fmac_f32_e32 v27, v7, v197
	ds_read_b128 v[186:189], v5 offset:25856
	s_waitcnt lgkmcnt(11)
	v_fmac_f32_e32 v26, v8, v202
	v_fmac_f32_e32 v27, v9, v203
	v_fmac_f32_e32 v26, v10, v204
	v_fmac_f32_e32 v27, v11, v205
	ds_read_b128 v[198:201], v5 offset:25904
	s_waitcnt lgkmcnt(11)
	v_fmac_f32_e32 v26, v12, v206
	v_fmac_f32_e32 v27, v13, v207
	v_fmac_f32_e32 v26, v14, v208
	v_fmac_f32_e32 v27, v15, v209
	ds_read_b128 v[194:197], v5 offset:25888
	v_add_f32_e32 v26, v26, v27
	s_waitcnt lgkmcnt(10)
	v_fma_f32 v27, v60, v214, 0
	v_fma_f32 v28, v0, v215, 0
	v_fmac_f32_e32 v27, v1, v216
	v_fmac_f32_e32 v28, v2, v217
	ds_read_b128 v[202:205], v5 offset:26112
	v_fmac_f32_e32 v27, v3, v228
	v_fmac_f32_e32 v28, v4, v229
	v_fmac_f32_e32 v27, v6, v230
	v_fmac_f32_e32 v28, v7, v231
	ds_read_b128 v[206:209], v5 offset:26128
	s_waitcnt lgkmcnt(10)
	v_fmac_f32_e32 v27, v8, v232
	v_fmac_f32_e32 v28, v9, v233
	v_fmac_f32_e32 v27, v10, v234
	v_fmac_f32_e32 v28, v11, v235
	ds_read_b128 v[214:217], v5 offset:26144
	v_fmac_f32_e32 v27, v12, v244
	v_fmac_f32_e32 v28, v13, v245
	v_fmac_f32_e32 v27, v14, v246
	v_fmac_f32_e32 v28, v15, v247
	ds_read_b128 v[228:231], v5 offset:26160
	v_add_f32_e32 v27, v27, v28
	v_sub_f32_e32 v26, v36, v26
	v_sub_f32_e32 v27, v37, v27
	s_mov_b64 exec, s[100:101]
	v_cvt_pk_bf16_f32 v238, -v6, s0
	global_store_short v[210:211], v238, off offset:768
	s_not_b64 exec, s[100:101]
	global_store_dword v[154:155], v6, off offset:1536
	s_mov_b64 exec, -1
	s_waitcnt lgkmcnt(11)
	v_fma_f32 v28, v60, v146, 0
	v_fma_f32 v29, v0, v147, 0
	v_fmac_f32_e32 v28, v1, v148
	v_fmac_f32_e32 v29, v2, v149
	ds_read_b128 v[232:235], v5 offset:26384
	s_waitcnt lgkmcnt(11)
	v_fmac_f32_e32 v28, v3, v150
	v_fmac_f32_e32 v29, v4, v151
	v_fmac_f32_e32 v28, v6, v152
	v_fmac_f32_e32 v29, v7, v153
	ds_read_b128 v[244:247], v5 offset:26368
	s_waitcnt lgkmcnt(11)
	v_fmac_f32_e32 v28, v8, v178
	v_fmac_f32_e32 v29, v9, v179
	v_fmac_f32_e32 v28, v10, v180
	v_fmac_f32_e32 v29, v11, v181
	ds_read_b128 v[146:149], v5 offset:26416
	s_waitcnt lgkmcnt(11)
	v_fmac_f32_e32 v28, v12, v182
	v_fmac_f32_e32 v29, v13, v183
	v_fmac_f32_e32 v28, v14, v184
	v_fmac_f32_e32 v29, v15, v185
	ds_read_b128 v[150:153], v5 offset:26400
	v_add_f32_e32 v28, v28, v29
	s_waitcnt lgkmcnt(10)
	v_fma_f32 v29, v60, v186, 0
	v_fma_f32 v36, v0, v187, 0
	v_fmac_f32_e32 v29, v1, v188
	v_fmac_f32_e32 v36, v2, v189
	ds_read_b128 v[178:181], v5 offset:26624
	v_fmac_f32_e32 v29, v3, v190
	v_fmac_f32_e32 v36, v4, v191
	v_fmac_f32_e32 v29, v6, v192
	v_fmac_f32_e32 v36, v7, v193
	ds_read_b128 v[182:185], v5 offset:26640
	s_waitcnt lgkmcnt(10)
	v_fmac_f32_e32 v29, v8, v194
	v_fmac_f32_e32 v36, v9, v195
	v_fmac_f32_e32 v29, v10, v196
	v_fmac_f32_e32 v36, v11, v197
	ds_read_b128 v[186:189], v5 offset:26656
	v_fmac_f32_e32 v29, v12, v198
	v_fmac_f32_e32 v36, v13, v199
	v_fmac_f32_e32 v29, v14, v200
	v_fmac_f32_e32 v36, v15, v201
	ds_read_b128 v[190:193], v5 offset:26672
	v_add_f32_e32 v29, v29, v36
	v_sub_f32_e32 v28, v38, v28
	v_sub_f32_e32 v29, v39, v29
	s_mov_b64 exec, s[100:101]
	v_cvt_pk_bf16_f32 v238, -v7, s0
	global_store_short v[210:211], v238, off offset:896
	s_not_b64 exec, s[100:101]
	global_store_dword v[154:155], v7, off offset:1792
	s_mov_b64 exec, -1
	s_waitcnt lgkmcnt(11)
	v_fma_f32 v52, v60, v202, 0
	v_fma_f32 v53, v0, v203, 0
	v_fmac_f32_e32 v52, v1, v204
	v_fmac_f32_e32 v53, v2, v205
	ds_read_b128 v[194:197], v5 offset:26896
	s_waitcnt lgkmcnt(11)
	v_fmac_f32_e32 v52, v3, v206
	v_fmac_f32_e32 v53, v4, v207
	v_fmac_f32_e32 v52, v6, v208
	v_fmac_f32_e32 v53, v7, v209
	ds_read_b128 v[198:201], v5 offset:26880
	s_waitcnt lgkmcnt(11)
	v_fmac_f32_e32 v52, v8, v214
	v_fmac_f32_e32 v53, v9, v215
	v_fmac_f32_e32 v52, v10, v216
	v_fmac_f32_e32 v53, v11, v217
	ds_read_b128 v[202:205], v5 offset:26928
	s_waitcnt lgkmcnt(11)
	v_fmac_f32_e32 v52, v12, v228
	v_fmac_f32_e32 v53, v13, v229
	v_fmac_f32_e32 v52, v14, v230
	v_fmac_f32_e32 v53, v15, v231
	ds_read_b128 v[206:209], v5 offset:26912
	v_add_f32_e32 v44, v52, v53
	v_sub_f32_e32 v72, v32, v44
	s_waitcnt lgkmcnt(10)
	v_fma_f32 v32, v60, v244, 0
	v_fma_f32 v40, v0, v245, 0
	v_fmac_f32_e32 v32, v1, v246
	v_fmac_f32_e32 v40, v2, v247
	ds_read_b128 v[214:217], v5 offset:27136
	v_fmac_f32_e32 v32, v3, v232
	v_fmac_f32_e32 v40, v4, v233
	v_fmac_f32_e32 v32, v6, v234
	v_fmac_f32_e32 v40, v7, v235
	ds_read_b128 v[228:231], v5 offset:27152
	s_waitcnt lgkmcnt(10)
	v_fmac_f32_e32 v32, v8, v150
	v_fmac_f32_e32 v40, v9, v151
	v_fmac_f32_e32 v32, v10, v152
	v_fmac_f32_e32 v40, v11, v153
	ds_read_b128 v[244:247], v5 offset:27168
	v_fmac_f32_e32 v32, v12, v146
	v_fmac_f32_e32 v40, v13, v147
	v_fmac_f32_e32 v32, v14, v148
	v_fmac_f32_e32 v40, v15, v149
	ds_read_b128 v[232:235], v5 offset:27184
	v_add_f32_e32 v32, v32, v40
	v_sub_f32_e32 v32, v33, v32
	s_mov_b64 exec, s[100:101]
	v_cvt_pk_bf16_f32 v238, -v8, s0
	global_store_short v[210:211], v238, off offset:1024
	s_not_b64 exec, s[100:101]
	global_store_dword v[154:155], v8, off offset:2048
	s_mov_b64 exec, -1
	s_waitcnt lgkmcnt(11)
	v_fma_f32 v33, v60, v178, 0
	v_fma_f32 v52, v0, v179, 0
	v_fmac_f32_e32 v33, v1, v180
	v_fmac_f32_e32 v52, v2, v181
	ds_read_b128 v[150:153], v5 offset:27408
	s_waitcnt lgkmcnt(11)
	v_fmac_f32_e32 v33, v3, v182
	v_fmac_f32_e32 v52, v4, v183
	v_fmac_f32_e32 v33, v6, v184
	v_fmac_f32_e32 v52, v7, v185
	ds_read_b128 v[146:149], v5 offset:27392
	s_waitcnt lgkmcnt(11)
	v_fmac_f32_e32 v33, v8, v186
	v_fmac_f32_e32 v52, v9, v187
	v_fmac_f32_e32 v33, v10, v188
	v_fmac_f32_e32 v52, v11, v189
	ds_read_b128 v[178:181], v5 offset:27440
	s_waitcnt lgkmcnt(11)
	v_fmac_f32_e32 v33, v12, v190
	v_fmac_f32_e32 v52, v13, v191
	v_fmac_f32_e32 v33, v14, v192
	v_fmac_f32_e32 v52, v15, v193
	ds_read_b128 v[182:185], v5 offset:27424
	v_add_f32_e32 v33, v33, v52
	v_sub_f32_e32 v33, v34, v33
	s_waitcnt lgkmcnt(10)
	v_fma_f32 v34, v60, v198, 0
	v_fma_f32 v40, v0, v199, 0
	v_fmac_f32_e32 v34, v1, v200
	v_fmac_f32_e32 v40, v2, v201
	ds_read_b128 v[186:189], v5 offset:27648
	v_fmac_f32_e32 v34, v3, v194
	v_fmac_f32_e32 v40, v4, v195
	v_fmac_f32_e32 v34, v6, v196
	v_fmac_f32_e32 v40, v7, v197
	ds_read_b128 v[190:193], v5 offset:27664
	s_waitcnt lgkmcnt(10)
	v_fmac_f32_e32 v34, v8, v206
	v_fmac_f32_e32 v40, v9, v207
	v_fmac_f32_e32 v34, v10, v208
	v_fmac_f32_e32 v40, v11, v209
	ds_read_b128 v[198:201], v5 offset:27680
	v_fmac_f32_e32 v34, v12, v202
	v_fmac_f32_e32 v40, v13, v203
	v_fmac_f32_e32 v34, v14, v204
	v_fmac_f32_e32 v40, v15, v205
	ds_read_b128 v[194:197], v5 offset:27696
	v_add_f32_e32 v34, v34, v40
	v_sub_f32_e32 v34, v35, v34
	s_mov_b64 exec, s[100:101]
	v_cvt_pk_bf16_f32 v238, -v9, s0
	global_store_short v[210:211], v238, off offset:1152
	s_not_b64 exec, s[100:101]
	global_store_dword v[154:155], v9, off offset:2304
	s_mov_b64 exec, -1
	s_waitcnt lgkmcnt(11)
	v_fma_f32 v35, v60, v214, 0
	v_fma_f32 v52, v0, v215, 0
	v_fmac_f32_e32 v35, v1, v216
	v_fmac_f32_e32 v52, v2, v217
	ds_read_b128 v[206:209], v5 offset:27920
	s_waitcnt lgkmcnt(11)
	v_fmac_f32_e32 v35, v3, v228
	v_fmac_f32_e32 v52, v4, v229
	v_fmac_f32_e32 v35, v6, v230
	v_fmac_f32_e32 v52, v7, v231
	ds_read_b128 v[202:205], v5 offset:27904
	s_waitcnt lgkmcnt(11)
	v_fmac_f32_e32 v35, v8, v244
	v_fmac_f32_e32 v52, v9, v245
	v_fmac_f32_e32 v35, v10, v246
	v_fmac_f32_e32 v52, v11, v247
	ds_read_b128 v[214:217], v5 offset:27952
	s_waitcnt lgkmcnt(11)
	v_fmac_f32_e32 v35, v12, v232
	v_fmac_f32_e32 v52, v13, v233
	v_fmac_f32_e32 v35, v14, v234
	v_fmac_f32_e32 v52, v15, v235
	ds_read_b128 v[228:231], v5 offset:27936
	v_add_f32_e32 v35, v35, v52
	v_sub_f32_e32 v35, v30, v35
	s_waitcnt lgkmcnt(10)
	v_fma_f32 v30, v60, v146, 0
	v_fma_f32 v40, v0, v147, 0
	v_fmac_f32_e32 v30, v1, v148
	v_fmac_f32_e32 v40, v2, v149
	ds_read_b128 v[244:247], v5 offset:28160
	v_fmac_f32_e32 v30, v3, v150
	v_fmac_f32_e32 v40, v4, v151
	v_fmac_f32_e32 v30, v6, v152
	v_fmac_f32_e32 v40, v7, v153
	ds_read_b128 v[232:235], v5 offset:28176
	s_waitcnt lgkmcnt(10)
	v_fmac_f32_e32 v30, v8, v182
	v_fmac_f32_e32 v40, v9, v183
	v_fmac_f32_e32 v30, v10, v184
	v_fmac_f32_e32 v40, v11, v185
	ds_read_b128 v[146:149], v5 offset:28192
	v_fmac_f32_e32 v30, v12, v178
	v_fmac_f32_e32 v40, v13, v179
	v_fmac_f32_e32 v30, v14, v180
	v_fmac_f32_e32 v40, v15, v181
	ds_read_b128 v[150:153], v5 offset:28208
	v_add_f32_e32 v30, v30, v40
	v_sub_f32_e32 v36, v31, v30
	s_mov_b64 exec, s[100:101]
	v_cvt_pk_bf16_f32 v238, -v10, s0
	global_store_short v[210:211], v238, off offset:1280
	s_not_b64 exec, s[100:101]
	global_store_dword v[154:155], v10, off offset:2560
	s_mov_b64 exec, -1
	s_waitcnt lgkmcnt(11)
	v_fma_f32 v30, v60, v186, 0
	v_fma_f32 v31, v0, v187, 0
	v_fmac_f32_e32 v30, v1, v188
	v_fmac_f32_e32 v31, v2, v189
	ds_read_b128 v[182:185], v5 offset:28432
	s_waitcnt lgkmcnt(11)
	v_fmac_f32_e32 v30, v3, v190
	v_fmac_f32_e32 v31, v4, v191
	v_fmac_f32_e32 v30, v6, v192
	v_fmac_f32_e32 v31, v7, v193
	ds_read_b128 v[178:181], v5 offset:28416
	s_waitcnt lgkmcnt(11)
	v_fmac_f32_e32 v30, v8, v198
	v_fmac_f32_e32 v31, v9, v199
	v_fmac_f32_e32 v30, v10, v200
	v_fmac_f32_e32 v31, v11, v201
	ds_read_b128 v[186:189], v5 offset:28464
	s_waitcnt lgkmcnt(11)
	v_fmac_f32_e32 v30, v12, v194
	v_fmac_f32_e32 v31, v13, v195
	v_fmac_f32_e32 v30, v14, v196
	v_fmac_f32_e32 v31, v15, v197
	ds_read_b128 v[190:193], v5 offset:28448
	v_add_f32_e32 v30, v30, v31
	v_sub_f32_e32 v37, v62, v30
	s_waitcnt lgkmcnt(10)
	v_fma_f32 v30, v60, v202, 0
	v_fma_f32 v31, v0, v203, 0
	v_fmac_f32_e32 v30, v1, v204
	v_fmac_f32_e32 v31, v2, v205
	ds_read_b128 v[198:201], v5 offset:28672
	v_fmac_f32_e32 v30, v3, v206
	v_fmac_f32_e32 v31, v4, v207
	v_fmac_f32_e32 v30, v6, v208
	v_fmac_f32_e32 v31, v7, v209
	ds_read_b128 v[194:197], v5 offset:28688
	s_waitcnt lgkmcnt(10)
	v_fmac_f32_e32 v30, v8, v228
	v_fmac_f32_e32 v31, v9, v229
	v_fmac_f32_e32 v30, v10, v230
	v_fmac_f32_e32 v31, v11, v231
	ds_read_b128 v[202:205], v5 offset:28704
	v_fmac_f32_e32 v30, v12, v214
	v_fmac_f32_e32 v31, v13, v215
	v_fmac_f32_e32 v30, v14, v216
	v_fmac_f32_e32 v31, v15, v217
	ds_read_b128 v[206:209], v5 offset:28720
	v_add_f32_e32 v30, v30, v31
	v_sub_f32_e32 v38, v63, v30
	s_mov_b64 exec, s[100:101]
	v_cvt_pk_bf16_f32 v238, -v11, s0
	global_store_short v[210:211], v238, off offset:1408
	s_not_b64 exec, s[100:101]
	global_store_dword v[154:155], v11, off offset:2816
	s_mov_b64 exec, -1
	s_waitcnt lgkmcnt(11)
	v_fma_f32 v30, v60, v244, 0
	v_fma_f32 v31, v0, v245, 0
	v_fmac_f32_e32 v30, v1, v246
	v_fmac_f32_e32 v31, v2, v247
	ds_read_b128 v[228:231], v5 offset:28944
	s_waitcnt lgkmcnt(11)
	v_fmac_f32_e32 v30, v3, v232
	v_fmac_f32_e32 v31, v4, v233
	v_fmac_f32_e32 v30, v6, v234
	v_fmac_f32_e32 v31, v7, v235
	ds_read_b128 v[214:217], v5 offset:28928
	s_waitcnt lgkmcnt(11)
	v_fmac_f32_e32 v30, v8, v146
	v_fmac_f32_e32 v31, v9, v147
	v_fmac_f32_e32 v30, v10, v148
	v_fmac_f32_e32 v31, v11, v149
	ds_read_b128 v[244:247], v5 offset:28976
	s_waitcnt lgkmcnt(11)
	v_fmac_f32_e32 v30, v12, v150
	v_fmac_f32_e32 v31, v13, v151
	v_fmac_f32_e32 v30, v14, v152
	v_fmac_f32_e32 v31, v15, v153
	ds_read_b128 v[232:235], v5 offset:28960
	v_add_f32_e32 v30, v30, v31
	v_sub_f32_e32 v39, v70, v30
	s_waitcnt lgkmcnt(10)
	v_fma_f32 v30, v60, v178, 0
	v_fma_f32 v31, v0, v179, 0
	v_fmac_f32_e32 v30, v1, v180
	v_fmac_f32_e32 v31, v2, v181
	ds_read_b128 v[146:149], v5 offset:29184
	v_fmac_f32_e32 v30, v3, v182
	v_fmac_f32_e32 v31, v4, v183
	v_fmac_f32_e32 v30, v6, v184
	v_fmac_f32_e32 v31, v7, v185
	ds_read_b128 v[150:153], v5 offset:29200
	s_waitcnt lgkmcnt(10)
	v_fmac_f32_e32 v30, v8, v190
	v_fmac_f32_e32 v31, v9, v191
	v_fmac_f32_e32 v30, v10, v192
	v_fmac_f32_e32 v31, v11, v193
	ds_read_b128 v[178:181], v5 offset:29216
	v_fmac_f32_e32 v30, v12, v186
	v_fmac_f32_e32 v31, v13, v187
	v_fmac_f32_e32 v30, v14, v188
	v_fmac_f32_e32 v31, v15, v189
	ds_read_b128 v[182:185], v5 offset:29232
	v_add_f32_e32 v30, v30, v31
	v_sub_f32_e32 v40, v71, v30
	s_mov_b64 exec, s[100:101]
	v_cvt_pk_bf16_f32 v238, -v12, s0
	global_store_short v[210:211], v238, off offset:1536
	s_not_b64 exec, s[100:101]
	global_store_dword v[154:155], v12, off offset:3072
	s_mov_b64 exec, -1
	s_waitcnt lgkmcnt(11)
	v_fma_f32 v30, v60, v198, 0
	v_fma_f32 v31, v0, v199, 0
	v_fmac_f32_e32 v30, v1, v200
	v_fmac_f32_e32 v31, v2, v201
	ds_read_b128 v[190:193], v5 offset:29456
	s_waitcnt lgkmcnt(11)
	v_fmac_f32_e32 v30, v3, v194
	v_fmac_f32_e32 v31, v4, v195
	v_fmac_f32_e32 v30, v6, v196
	v_fmac_f32_e32 v31, v7, v197
	ds_read_b128 v[186:189], v5 offset:29440
	s_waitcnt lgkmcnt(11)
	v_fmac_f32_e32 v30, v8, v202
	v_fmac_f32_e32 v31, v9, v203
	v_fmac_f32_e32 v30, v10, v204
	v_fmac_f32_e32 v31, v11, v205
	ds_read_b128 v[198:201], v5 offset:29488
	s_waitcnt lgkmcnt(11)
	v_fmac_f32_e32 v30, v12, v206
	v_fmac_f32_e32 v31, v13, v207
	v_fmac_f32_e32 v30, v14, v208
	v_fmac_f32_e32 v31, v15, v209
	ds_read_b128 v[194:197], v5 offset:29472
	v_add_f32_e32 v30, v30, v31
	v_sub_f32_e32 v41, v58, v30
	s_waitcnt lgkmcnt(10)
	v_fma_f32 v30, v60, v214, 0
	v_fma_f32 v31, v0, v215, 0
	v_fmac_f32_e32 v30, v1, v216
	v_fmac_f32_e32 v31, v2, v217
	ds_read_b128 v[202:205], v5 offset:29696
	v_fmac_f32_e32 v30, v3, v228
	v_fmac_f32_e32 v31, v4, v229
	v_fmac_f32_e32 v30, v6, v230
	v_fmac_f32_e32 v31, v7, v231
	ds_read_b128 v[206:209], v5 offset:29712
	s_waitcnt lgkmcnt(10)
	v_fmac_f32_e32 v30, v8, v232
	v_fmac_f32_e32 v31, v9, v233
	v_fmac_f32_e32 v30, v10, v234
	v_fmac_f32_e32 v31, v11, v235
	ds_read_b128 v[214:217], v5 offset:29728
	v_fmac_f32_e32 v30, v12, v244
	v_fmac_f32_e32 v31, v13, v245
	v_fmac_f32_e32 v30, v14, v246
	v_fmac_f32_e32 v31, v15, v247
	ds_read_b128 v[228:231], v5 offset:29744
	v_add_f32_e32 v30, v30, v31
	v_sub_f32_e32 v42, v59, v30
	s_mov_b64 exec, s[100:101]
	v_cvt_pk_bf16_f32 v238, -v13, s0
	global_store_short v[210:211], v238, off offset:1664
	s_not_b64 exec, s[100:101]
	global_store_dword v[154:155], v13, off offset:3328
	s_mov_b64 exec, -1
	s_waitcnt lgkmcnt(11)
	v_fma_f32 v30, v60, v146, 0
	v_fma_f32 v31, v0, v147, 0
	v_fmac_f32_e32 v30, v1, v148
	v_fmac_f32_e32 v31, v2, v149
	ds_read_b128 v[232:235], v5 offset:29968
	s_waitcnt lgkmcnt(11)
	v_fmac_f32_e32 v30, v3, v150
	v_fmac_f32_e32 v31, v4, v151
	v_fmac_f32_e32 v30, v6, v152
	v_fmac_f32_e32 v31, v7, v153
	ds_read_b128 v[244:247], v5 offset:29952
	s_waitcnt lgkmcnt(11)
	v_fmac_f32_e32 v30, v8, v178
	v_fmac_f32_e32 v31, v9, v179
	v_fmac_f32_e32 v30, v10, v180
	v_fmac_f32_e32 v31, v11, v181
	ds_read_b128 v[146:149], v5 offset:30000
	s_waitcnt lgkmcnt(11)
	v_fmac_f32_e32 v30, v12, v182
	v_fmac_f32_e32 v31, v13, v183
	v_fmac_f32_e32 v30, v14, v184
	v_fmac_f32_e32 v31, v15, v185
	ds_read_b128 v[150:153], v5 offset:29984
	v_add_f32_e32 v30, v30, v31
	v_sub_f32_e32 v43, v56, v30
	s_waitcnt lgkmcnt(10)
	v_fma_f32 v30, v60, v186, 0
	v_fma_f32 v31, v0, v187, 0
	v_fmac_f32_e32 v30, v1, v188
	v_fmac_f32_e32 v31, v2, v189
	ds_read_b128 v[178:181], v5 offset:30208
	v_fmac_f32_e32 v30, v3, v190
	v_fmac_f32_e32 v31, v4, v191
	v_fmac_f32_e32 v30, v6, v192
	v_fmac_f32_e32 v31, v7, v193
	ds_read_b128 v[182:185], v5 offset:30224
	s_waitcnt lgkmcnt(10)
	v_fmac_f32_e32 v30, v8, v194
	v_fmac_f32_e32 v31, v9, v195
	v_fmac_f32_e32 v30, v10, v196
	v_fmac_f32_e32 v31, v11, v197
	ds_read_b128 v[186:189], v5 offset:30240
	v_fmac_f32_e32 v30, v12, v198
	v_fmac_f32_e32 v31, v13, v199
	v_fmac_f32_e32 v30, v14, v200
	v_fmac_f32_e32 v31, v15, v201
	ds_read_b128 v[190:193], v5 offset:30256
	v_add_f32_e32 v30, v30, v31
	v_sub_f32_e32 v44, v57, v30
	s_mov_b64 exec, s[100:101]
	v_cvt_pk_bf16_f32 v238, -v14, s0
	global_store_short v[210:211], v238, off offset:1792
	s_not_b64 exec, s[100:101]
	global_store_dword v[154:155], v14, off offset:3584
	s_mov_b64 exec, -1
	s_waitcnt lgkmcnt(11)
	v_fma_f32 v30, v60, v202, 0
	v_fma_f32 v31, v0, v203, 0
	v_fmac_f32_e32 v30, v1, v204
	v_fmac_f32_e32 v31, v2, v205
	ds_read_b128 v[194:197], v5 offset:30480
	s_waitcnt lgkmcnt(11)
	v_fmac_f32_e32 v30, v3, v206
	v_fmac_f32_e32 v31, v4, v207
	v_fmac_f32_e32 v30, v6, v208
	v_fmac_f32_e32 v31, v7, v209
	ds_read_b128 v[198:201], v5 offset:30464
	s_waitcnt lgkmcnt(11)
	v_fmac_f32_e32 v30, v8, v214
	v_fmac_f32_e32 v31, v9, v215
	v_fmac_f32_e32 v30, v10, v216
	v_fmac_f32_e32 v31, v11, v217
	ds_read_b128 v[202:205], v5 offset:30512
	s_waitcnt lgkmcnt(11)
	v_fmac_f32_e32 v30, v12, v228
	v_fmac_f32_e32 v31, v13, v229
	v_fmac_f32_e32 v30, v14, v230
	v_fmac_f32_e32 v31, v15, v231
	ds_read_b128 v[206:209], v5 offset:30496
	v_add_f32_e32 v30, v30, v31
	v_sub_f32_e32 v45, v84, v30
	s_waitcnt lgkmcnt(10)
	v_fma_f32 v30, v60, v244, 0
	v_fma_f32 v31, v0, v245, 0
	v_fmac_f32_e32 v30, v1, v246
	v_fmac_f32_e32 v31, v2, v247
	ds_read_b128 v[214:217], v5 offset:30720
	v_fmac_f32_e32 v30, v3, v232
	v_fmac_f32_e32 v31, v4, v233
	v_fmac_f32_e32 v30, v6, v234
	v_fmac_f32_e32 v31, v7, v235
	ds_read_b128 v[228:231], v5 offset:30736
	s_waitcnt lgkmcnt(10)
	v_fmac_f32_e32 v30, v8, v150
	v_fmac_f32_e32 v31, v9, v151
	v_fmac_f32_e32 v30, v10, v152
	v_fmac_f32_e32 v31, v11, v153
	ds_read_b128 v[244:247], v5 offset:30752
	v_fmac_f32_e32 v30, v12, v146
	v_fmac_f32_e32 v31, v13, v147
	v_fmac_f32_e32 v30, v14, v148
	v_fmac_f32_e32 v31, v15, v149
	ds_read_b128 v[232:235], v5 offset:30768
	v_add_f32_e32 v30, v30, v31
	v_sub_f32_e32 v46, v85, v30
	s_mov_b64 exec, s[100:101]
	v_cvt_pk_bf16_f32 v238, -v15, s0
	global_store_short v[210:211], v238, off offset:1920
	s_not_b64 exec, s[100:101]
	global_store_dword v[154:155], v15, off offset:3840
	s_mov_b64 exec, -1
	s_waitcnt lgkmcnt(11)
	v_fma_f32 v30, v60, v178, 0
	v_fma_f32 v31, v0, v179, 0
	v_fmac_f32_e32 v30, v1, v180
	v_fmac_f32_e32 v31, v2, v181
	ds_read_b128 v[150:153], v5 offset:30992
	s_waitcnt lgkmcnt(11)
	v_fmac_f32_e32 v30, v3, v182
	v_fmac_f32_e32 v31, v4, v183
	v_fmac_f32_e32 v30, v6, v184
	v_fmac_f32_e32 v31, v7, v185
	ds_read_b128 v[146:149], v5 offset:30976
	s_waitcnt lgkmcnt(11)
	v_fmac_f32_e32 v30, v8, v186
	v_fmac_f32_e32 v31, v9, v187
	v_fmac_f32_e32 v30, v10, v188
	v_fmac_f32_e32 v31, v11, v189
	ds_read_b128 v[178:181], v5 offset:31024
	s_waitcnt lgkmcnt(11)
	v_fmac_f32_e32 v30, v12, v190
	v_fmac_f32_e32 v31, v13, v191
	v_fmac_f32_e32 v30, v14, v192
	v_fmac_f32_e32 v31, v15, v193
	ds_read_b128 v[182:185], v5 offset:31008
	v_add_f32_e32 v30, v30, v31
	v_sub_f32_e32 v47, v78, v30
	s_waitcnt lgkmcnt(10)
	v_fma_f32 v30, v60, v198, 0
	v_fma_f32 v31, v0, v199, 0
	v_fmac_f32_e32 v30, v1, v200
	v_fmac_f32_e32 v31, v2, v201
	ds_read_b128 v[186:189], v5 offset:31232
	v_fmac_f32_e32 v30, v3, v194
	v_fmac_f32_e32 v31, v4, v195
	v_fmac_f32_e32 v30, v6, v196
	v_fmac_f32_e32 v31, v7, v197
	ds_read_b128 v[190:193], v5 offset:31248
	s_waitcnt lgkmcnt(10)
	v_fmac_f32_e32 v30, v8, v206
	v_fmac_f32_e32 v31, v9, v207
	v_fmac_f32_e32 v30, v10, v208
	v_fmac_f32_e32 v31, v11, v209
	ds_read_b128 v[198:201], v5 offset:31264
	v_fmac_f32_e32 v30, v12, v202
	v_fmac_f32_e32 v31, v13, v203
	v_fmac_f32_e32 v30, v14, v204
	v_fmac_f32_e32 v31, v15, v205
	ds_read_b128 v[194:197], v5 offset:31280
	v_add_f32_e32 v30, v30, v31
	v_sub_f32_e32 v48, v79, v30
	s_waitcnt lgkmcnt(11)
	v_fma_f32 v30, v60, v214, 0
	v_fma_f32 v31, v0, v215, 0
	v_fmac_f32_e32 v30, v1, v216
	v_fmac_f32_e32 v31, v2, v217
	ds_read_b128 v[206:209], v5 offset:31504
	s_waitcnt lgkmcnt(11)
	v_fmac_f32_e32 v30, v3, v228
	v_fmac_f32_e32 v31, v4, v229
	v_fmac_f32_e32 v30, v6, v230
	v_fmac_f32_e32 v31, v7, v231
	ds_read_b128 v[202:205], v5 offset:31488
	s_waitcnt lgkmcnt(11)
	v_fmac_f32_e32 v30, v8, v244
	v_fmac_f32_e32 v31, v9, v245
	v_fmac_f32_e32 v30, v10, v246
	v_fmac_f32_e32 v31, v11, v247
	ds_read_b128 v[214:217], v5 offset:31536
	s_waitcnt lgkmcnt(11)
	v_fmac_f32_e32 v30, v12, v232
	v_fmac_f32_e32 v31, v13, v233
	v_fmac_f32_e32 v30, v14, v234
	v_fmac_f32_e32 v31, v15, v235
	ds_read_b128 v[228:231], v5 offset:31520
	v_add_f32_e32 v30, v30, v31
	v_sub_f32_e32 v49, v76, v30
	s_waitcnt lgkmcnt(10)
	v_fma_f32 v30, v60, v146, 0
	v_fma_f32 v31, v0, v147, 0
	v_fmac_f32_e32 v30, v1, v148
	v_fmac_f32_e32 v31, v2, v149
	ds_read_b128 v[244:247], v5 offset:31744
	v_fmac_f32_e32 v30, v3, v150
	v_fmac_f32_e32 v31, v4, v151
	v_fmac_f32_e32 v30, v6, v152
	v_fmac_f32_e32 v31, v7, v153
	ds_read_b128 v[232:235], v5 offset:31760
	s_waitcnt lgkmcnt(10)
	v_fmac_f32_e32 v30, v8, v182
	v_fmac_f32_e32 v31, v9, v183
	v_fmac_f32_e32 v30, v10, v184
	v_fmac_f32_e32 v31, v11, v185
	ds_read_b128 v[146:149], v5 offset:31776
	v_fmac_f32_e32 v30, v12, v178
	v_fmac_f32_e32 v31, v13, v179
	v_fmac_f32_e32 v30, v14, v180
	v_fmac_f32_e32 v31, v15, v181
	ds_read_b128 v[150:153], v5 offset:31792
	v_add_f32_e32 v30, v30, v31
	v_sub_f32_e32 v50, v77, v30
	s_waitcnt lgkmcnt(11)
	v_fma_f32 v30, v60, v186, 0
	v_fma_f32 v31, v0, v187, 0
	v_fmac_f32_e32 v30, v1, v188
	v_fmac_f32_e32 v31, v2, v189
	ds_read_b128 v[182:185], v5 offset:32016
	s_waitcnt lgkmcnt(11)
	v_fmac_f32_e32 v30, v3, v190
	v_fmac_f32_e32 v31, v4, v191
	v_fmac_f32_e32 v30, v6, v192
	v_fmac_f32_e32 v31, v7, v193
	ds_read_b128 v[178:181], v5 offset:32000
	s_waitcnt lgkmcnt(11)
	v_fmac_f32_e32 v30, v8, v198
	v_fmac_f32_e32 v31, v9, v199
	v_fmac_f32_e32 v30, v10, v200
	v_fmac_f32_e32 v31, v11, v201
	ds_read_b128 v[186:189], v5 offset:32048
	s_waitcnt lgkmcnt(11)
	v_fmac_f32_e32 v30, v12, v194
	v_fmac_f32_e32 v31, v13, v195
	v_fmac_f32_e32 v30, v14, v196
	v_fmac_f32_e32 v31, v15, v197
	ds_read_b128 v[190:193], v5 offset:32032
	v_add_f32_e32 v30, v30, v31
	v_sub_f32_e32 v51, v74, v30
	s_waitcnt lgkmcnt(10)
	v_fma_f32 v30, v60, v202, 0
	v_fma_f32 v31, v0, v203, 0
	v_fmac_f32_e32 v30, v1, v204
	v_fmac_f32_e32 v31, v2, v205
	ds_read_b128 v[198:201], v5 offset:32256
	v_fmac_f32_e32 v30, v3, v206
	v_fmac_f32_e32 v31, v4, v207
	v_fmac_f32_e32 v30, v6, v208
	v_fmac_f32_e32 v31, v7, v209
	ds_read_b128 v[194:197], v5 offset:32272
	s_waitcnt lgkmcnt(10)
	v_fmac_f32_e32 v30, v8, v228
	v_fmac_f32_e32 v31, v9, v229
	v_fmac_f32_e32 v30, v10, v230
	v_fmac_f32_e32 v31, v11, v231
	ds_read_b128 v[202:205], v5 offset:32288
	v_fmac_f32_e32 v30, v12, v214
	v_fmac_f32_e32 v31, v13, v215
	v_fmac_f32_e32 v30, v14, v216
	v_fmac_f32_e32 v31, v15, v217
	ds_read_b128 v[206:209], v5 offset:32304
	v_add_f32_e32 v30, v30, v31
	v_sub_f32_e32 v52, v75, v30
	s_waitcnt lgkmcnt(11)
	v_fma_f32 v30, v60, v244, 0
	v_fma_f32 v31, v0, v245, 0
	v_fmac_f32_e32 v30, v1, v246
	v_fmac_f32_e32 v31, v2, v247
	ds_read_b128 v[228:231], v5 offset:32528
	s_waitcnt lgkmcnt(11)
	v_fmac_f32_e32 v30, v3, v232
	v_fmac_f32_e32 v31, v4, v233
	v_fmac_f32_e32 v30, v6, v234
	v_fmac_f32_e32 v31, v7, v235
	ds_read_b128 v[214:217], v5 offset:32512
	s_waitcnt lgkmcnt(11)
	v_fmac_f32_e32 v30, v8, v146
	v_fmac_f32_e32 v31, v9, v147
	v_fmac_f32_e32 v30, v10, v148
	v_fmac_f32_e32 v31, v11, v149
	ds_read_b128 v[244:247], v5 offset:32560
	s_waitcnt lgkmcnt(11)
	v_fmac_f32_e32 v30, v12, v150
	v_fmac_f32_e32 v31, v13, v151
	v_fmac_f32_e32 v30, v14, v152
	v_fmac_f32_e32 v31, v15, v153
	ds_read_b128 v[232:235], v5 offset:32544
	v_add_f32_e32 v30, v30, v31
	v_sub_f32_e32 v53, v92, v30
	s_waitcnt lgkmcnt(10)
	v_fma_f32 v30, v60, v178, 0
	v_fma_f32 v31, v0, v179, 0
	v_fmac_f32_e32 v30, v1, v180
	v_fmac_f32_e32 v31, v2, v181
	ds_read_b128 v[146:149], v5 offset:32768
	v_fmac_f32_e32 v30, v3, v182
	v_fmac_f32_e32 v31, v4, v183
	v_fmac_f32_e32 v30, v6, v184
	v_fmac_f32_e32 v31, v7, v185
	ds_read_b128 v[150:153], v5 offset:32784
	s_waitcnt lgkmcnt(10)
	v_fmac_f32_e32 v30, v8, v190
	v_fmac_f32_e32 v31, v9, v191
	v_fmac_f32_e32 v30, v10, v192
	v_fmac_f32_e32 v31, v11, v193
	ds_read_b128 v[178:181], v5 offset:32800
	v_fmac_f32_e32 v30, v12, v186
	v_fmac_f32_e32 v31, v13, v187
	v_fmac_f32_e32 v30, v14, v188
	v_fmac_f32_e32 v31, v15, v189
	ds_read_b128 v[182:185], v5 offset:32816
	v_add_f32_e32 v30, v30, v31
	v_sub_f32_e32 v54, v93, v30
	s_waitcnt lgkmcnt(11)
	v_fma_f32 v30, v60, v198, 0
	v_fma_f32 v31, v0, v199, 0
	v_fmac_f32_e32 v30, v1, v200
	v_fmac_f32_e32 v31, v2, v201
	ds_read_b128 v[190:193], v5 offset:33040
	s_waitcnt lgkmcnt(11)
	v_fmac_f32_e32 v30, v3, v194
	v_fmac_f32_e32 v31, v4, v195
	v_fmac_f32_e32 v30, v6, v196
	v_fmac_f32_e32 v31, v7, v197
	ds_read_b128 v[186:189], v5 offset:33024
	s_waitcnt lgkmcnt(11)
	v_fmac_f32_e32 v30, v8, v202
	v_fmac_f32_e32 v31, v9, v203
	v_fmac_f32_e32 v30, v10, v204
	v_fmac_f32_e32 v31, v11, v205
	ds_read_b128 v[198:201], v5 offset:33072
	s_waitcnt lgkmcnt(11)
	v_fmac_f32_e32 v30, v12, v206
	v_fmac_f32_e32 v31, v13, v207
	v_fmac_f32_e32 v30, v14, v208
	v_fmac_f32_e32 v31, v15, v209
	ds_read_b128 v[194:197], v5 offset:33056
	v_add_f32_e32 v30, v30, v31
	v_sub_f32_e32 v55, v88, v30
	s_waitcnt lgkmcnt(10)
	v_fma_f32 v30, v60, v214, 0
	v_fma_f32 v31, v0, v215, 0
	v_fmac_f32_e32 v30, v1, v216
	v_fmac_f32_e32 v31, v2, v217
	ds_read_b128 v[202:205], v5 offset:33280
	v_fmac_f32_e32 v30, v3, v228
	v_fmac_f32_e32 v31, v4, v229
	v_fmac_f32_e32 v30, v6, v230
	v_fmac_f32_e32 v31, v7, v231
	ds_read_b128 v[206:209], v5 offset:33296
	s_waitcnt lgkmcnt(10)
	v_fmac_f32_e32 v30, v8, v232
	v_fmac_f32_e32 v31, v9, v233
	v_fmac_f32_e32 v30, v10, v234
	v_fmac_f32_e32 v31, v11, v235
	ds_read_b128 v[214:217], v5 offset:33312
	v_fmac_f32_e32 v30, v12, v244
	v_fmac_f32_e32 v31, v13, v245
	v_fmac_f32_e32 v30, v14, v246
	v_fmac_f32_e32 v31, v15, v247
	ds_read_b128 v[228:231], v5 offset:33328
	v_add_f32_e32 v30, v30, v31
	v_sub_f32_e32 v56, v89, v30
	s_waitcnt lgkmcnt(11)
	v_fma_f32 v30, v60, v146, 0
	v_fma_f32 v31, v0, v147, 0
	v_fmac_f32_e32 v30, v1, v148
	v_fmac_f32_e32 v31, v2, v149
	ds_read_b128 v[232:235], v5 offset:33552
	s_waitcnt lgkmcnt(11)
	v_fmac_f32_e32 v30, v3, v150
	v_fmac_f32_e32 v31, v4, v151
	v_fmac_f32_e32 v30, v6, v152
	v_fmac_f32_e32 v31, v7, v153
	ds_read_b128 v[244:247], v5 offset:33536
	s_waitcnt lgkmcnt(11)
	v_fmac_f32_e32 v30, v8, v178
	v_fmac_f32_e32 v31, v9, v179
	v_fmac_f32_e32 v30, v10, v180
	v_fmac_f32_e32 v31, v11, v181
	ds_read_b128 v[146:149], v5 offset:33584
	s_waitcnt lgkmcnt(11)
	v_fmac_f32_e32 v30, v12, v182
	v_fmac_f32_e32 v31, v13, v183
	v_fmac_f32_e32 v30, v14, v184
	v_fmac_f32_e32 v31, v15, v185
	ds_read_b128 v[150:153], v5 offset:33568
	v_add_f32_e32 v30, v30, v31
	v_sub_f32_e32 v57, v94, v30
	s_waitcnt lgkmcnt(10)
	v_fma_f32 v30, v60, v186, 0
	v_fma_f32 v31, v0, v187, 0
	v_fmac_f32_e32 v30, v1, v188
	v_fmac_f32_e32 v31, v2, v189
	ds_read_b128 v[178:181], v5 offset:33792
	v_fmac_f32_e32 v30, v3, v190
	v_fmac_f32_e32 v31, v4, v191
	v_fmac_f32_e32 v30, v6, v192
	v_fmac_f32_e32 v31, v7, v193
	ds_read_b128 v[182:185], v5 offset:33808
	s_waitcnt lgkmcnt(10)
	v_fmac_f32_e32 v30, v8, v194
	v_fmac_f32_e32 v31, v9, v195
	v_fmac_f32_e32 v30, v10, v196
	v_fmac_f32_e32 v31, v11, v197
	ds_read_b128 v[186:189], v5 offset:33824
	v_fmac_f32_e32 v30, v12, v198
	v_fmac_f32_e32 v31, v13, v199
	v_fmac_f32_e32 v30, v14, v200
	v_fmac_f32_e32 v31, v15, v201
	ds_read_b128 v[190:193], v5 offset:33840
	v_add_f32_e32 v30, v30, v31
	v_sub_f32_e32 v58, v95, v30
	s_waitcnt lgkmcnt(11)
	v_fma_f32 v30, v60, v202, 0
	v_fma_f32 v31, v0, v203, 0
	v_fmac_f32_e32 v30, v1, v204
	v_fmac_f32_e32 v31, v2, v205
	ds_read_b128 v[194:197], v5 offset:34064
	s_waitcnt lgkmcnt(11)
	v_fmac_f32_e32 v30, v3, v206
	v_fmac_f32_e32 v31, v4, v207
	v_fmac_f32_e32 v30, v6, v208
	v_fmac_f32_e32 v31, v7, v209
	ds_read_b128 v[198:201], v5 offset:34048
	s_waitcnt lgkmcnt(11)
	v_fmac_f32_e32 v30, v8, v214
	v_fmac_f32_e32 v31, v9, v215
	v_fmac_f32_e32 v30, v10, v216
	v_fmac_f32_e32 v31, v11, v217
	ds_read_b128 v[202:205], v5 offset:34096
	s_waitcnt lgkmcnt(11)
	v_fmac_f32_e32 v30, v12, v228
	v_fmac_f32_e32 v31, v13, v229
	v_fmac_f32_e32 v30, v14, v230
	v_fmac_f32_e32 v31, v15, v231
	ds_read_b128 v[206:209], v5 offset:34080
	v_add_f32_e32 v30, v30, v31
	v_sub_f32_e32 v59, v90, v30
	s_waitcnt lgkmcnt(10)
	v_fma_f32 v30, v60, v244, 0
	v_fma_f32 v31, v0, v245, 0
	v_fmac_f32_e32 v30, v1, v246
	v_fmac_f32_e32 v31, v2, v247
	ds_read_b128 v[214:217], v5 offset:34304
	v_fmac_f32_e32 v30, v3, v232
	v_fmac_f32_e32 v31, v4, v233
	v_fmac_f32_e32 v30, v6, v234
	v_fmac_f32_e32 v31, v7, v235
	ds_read_b128 v[228:231], v5 offset:34320
	s_waitcnt lgkmcnt(10)
	v_fmac_f32_e32 v30, v8, v150
	v_fmac_f32_e32 v31, v9, v151
	v_fmac_f32_e32 v30, v10, v152
	v_fmac_f32_e32 v31, v11, v153
	ds_read_b128 v[244:247], v5 offset:34336
	v_fmac_f32_e32 v30, v12, v146
	v_fmac_f32_e32 v31, v13, v147
	v_fmac_f32_e32 v30, v14, v148
	v_fmac_f32_e32 v31, v15, v149
	ds_read_b128 v[232:235], v5 offset:34352
	v_add_f32_e32 v30, v30, v31
	v_sub_f32_e32 v61, v91, v30
	s_waitcnt lgkmcnt(11)
	v_fma_f32 v30, v60, v178, 0
	v_fma_f32 v31, v0, v179, 0
	v_fmac_f32_e32 v30, v1, v180
	v_fmac_f32_e32 v31, v2, v181
	ds_read_b128 v[150:153], v5 offset:34576
	s_waitcnt lgkmcnt(11)
	v_fmac_f32_e32 v30, v3, v182
	v_fmac_f32_e32 v31, v4, v183
	v_fmac_f32_e32 v30, v6, v184
	v_fmac_f32_e32 v31, v7, v185
	ds_read_b128 v[146:149], v5 offset:34560
	s_waitcnt lgkmcnt(11)
	v_fmac_f32_e32 v30, v8, v186
	v_fmac_f32_e32 v31, v9, v187
	v_fmac_f32_e32 v30, v10, v188
	v_fmac_f32_e32 v31, v11, v189
	ds_read_b128 v[178:181], v5 offset:34608
	s_waitcnt lgkmcnt(11)
	v_fmac_f32_e32 v30, v12, v190
	v_fmac_f32_e32 v31, v13, v191
	v_fmac_f32_e32 v30, v14, v192
	v_fmac_f32_e32 v31, v15, v193
	ds_read_b128 v[182:185], v5 offset:34592
	v_add_f32_e32 v30, v30, v31
	v_sub_f32_e32 v62, v96, v30
	s_waitcnt lgkmcnt(10)
	v_fma_f32 v30, v60, v198, 0
	v_fma_f32 v31, v0, v199, 0
	v_fmac_f32_e32 v30, v1, v200
	v_fmac_f32_e32 v31, v2, v201
	ds_read_b128 v[186:189], v5 offset:22848
	v_fmac_f32_e32 v30, v3, v194
	v_fmac_f32_e32 v31, v4, v195
	v_fmac_f32_e32 v30, v6, v196
	v_fmac_f32_e32 v31, v7, v197
	ds_read_b128 v[190:193], v5 offset:23104
	s_waitcnt lgkmcnt(10)
	v_fmac_f32_e32 v30, v8, v206
	v_fmac_f32_e32 v31, v9, v207
	v_fmac_f32_e32 v30, v10, v208
	v_fmac_f32_e32 v31, v11, v209
	ds_read_b128 v[198:201], v5 offset:23360
	v_fmac_f32_e32 v30, v12, v202
	v_fmac_f32_e32 v31, v13, v203
	v_fmac_f32_e32 v30, v14, v204
	v_fmac_f32_e32 v31, v15, v205
	ds_read_b128 v[194:197], v5 offset:23616
	v_add_f32_e32 v30, v30, v31
	v_sub_f32_e32 v63, v97, v30
	s_waitcnt lgkmcnt(11)
	v_fma_f32 v30, v60, v214, 0
	v_fma_f32 v31, v0, v215, 0
	v_fmac_f32_e32 v30, v1, v216
	v_fmac_f32_e32 v31, v2, v217
	ds_read_b128 v[206:209], v5 offset:23872
	s_waitcnt lgkmcnt(11)
	v_fmac_f32_e32 v30, v3, v228
	v_fmac_f32_e32 v31, v4, v229
	v_fmac_f32_e32 v30, v6, v230
	v_fmac_f32_e32 v31, v7, v231
	ds_read_b128 v[202:205], v5 offset:23888
	s_waitcnt lgkmcnt(11)
	v_fmac_f32_e32 v30, v8, v244
	v_fmac_f32_e32 v31, v9, v245
	v_fmac_f32_e32 v30, v10, v246
	v_fmac_f32_e32 v31, v11, v247
	ds_read_b128 v[214:217], v5 offset:24128
	s_waitcnt lgkmcnt(11)
	v_fmac_f32_e32 v30, v12, v232
	v_fmac_f32_e32 v31, v13, v233
	v_fmac_f32_e32 v30, v14, v234
	v_fmac_f32_e32 v31, v15, v235
	ds_read_b128 v[228:231], v5 offset:24144
	v_add_f32_e32 v30, v30, v31
	v_sub_f32_e32 v70, v98, v30
	s_waitcnt lgkmcnt(10)
	v_fma_f32 v30, v60, v146, 0
	v_fma_f32 v31, v0, v147, 0
	v_fmac_f32_e32 v30, v1, v148
	v_fmac_f32_e32 v31, v2, v149
	ds_read_b128 v[244:247], v5 offset:24384
	v_fmac_f32_e32 v30, v3, v150
	v_fmac_f32_e32 v31, v4, v151
	v_fmac_f32_e32 v30, v6, v152
	v_fmac_f32_e32 v31, v7, v153
	ds_read_b128 v[232:235], v5 offset:24400
	s_waitcnt lgkmcnt(10)
	v_fmac_f32_e32 v30, v8, v182
	v_fmac_f32_e32 v31, v9, v183
	v_fmac_f32_e32 v30, v10, v184
	v_fmac_f32_e32 v31, v11, v185
	ds_read_b128 v[146:149], v5 offset:24640
	v_fmac_f32_e32 v30, v12, v178
	v_fmac_f32_e32 v31, v13, v179
	v_fmac_f32_e32 v30, v14, v180
	v_fmac_f32_e32 v31, v15, v181
	ds_read_b128 v[150:153], v5 offset:24656
	v_add_f32_e32 v30, v30, v31
	v_sub_f32_e32 v71, v99, v30
	s_waitcnt lgkmcnt(11)
	v_fma_f32 v30, -v16, v186, v17
	v_fma_f32 v17, -v17, v187, v30
	v_fma_f32 v17, -v18, v188, v17
	v_fma_f32 v17, -v19, v189, v17
	ds_read_b128 v[182:185], v5 offset:24896
	s_waitcnt lgkmcnt(11)
	v_fma_f32 v30, -v16, v190, v18
	v_fma_f32 v30, -v191, v17, v30
	v_fma_f32 v18, -v18, v192, v30
	v_fma_f32 v18, -v19, v193, v18
	ds_read_b128 v[178:181], v5 offset:24912
	s_waitcnt lgkmcnt(11)
	v_fma_f32 v30, -v16, v198, v19
	v_fma_f32 v30, -v199, v17, v30
	v_fma_f32 v30, -v200, v18, v30
	v_fma_f32 v19, -v19, v201, v30
	ds_read_b128 v[186:189], v5 offset:24928
	s_waitcnt lgkmcnt(11)
	v_fma_f32 v20, -v16, v194, v20
	v_fma_f32 v20, -v195, v17, v20
	v_fma_f32 v20, -v196, v18, v20
	v_fma_f32 v20, -v197, v19, v20
	ds_read_b128 v[190:193], v5 offset:25152
	s_waitcnt lgkmcnt(11)
	v_fma_f32 v30, -v16, v206, v21
	v_fma_f32 v30, -v207, v17, v30
	v_fma_f32 v30, -v208, v18, v30
	v_fma_f32 v30, -v209, v19, v30
	ds_read_b128 v[198:201], v5 offset:25168
	s_waitcnt lgkmcnt(11)
	v_fma_f32 v30, -v202, v20, v30
	v_fma_f32 v21, -v21, v203, v30
	v_fma_f32 v21, -v22, v204, v21
	v_fma_f32 v21, -v23, v205, v21
	ds_read_b128 v[194:197], v5 offset:25184
	s_waitcnt lgkmcnt(11)
	v_fma_f32 v30, -v16, v214, v22
	v_fma_f32 v30, -v17, v215, v30
	v_fma_f32 v30, -v216, v18, v30
	v_fma_f32 v30, -v217, v19, v30
	ds_read_b128 v[206:209], v5 offset:25408
	s_waitcnt lgkmcnt(11)
	v_fma_f32 v30, -v228, v20, v30
	v_fma_f32 v30, -v229, v21, v30
	v_fma_f32 v22, -v22, v230, v30
	v_fma_f32 v22, -v23, v231, v22
	ds_read_b128 v[202:205], v5 offset:25424
	s_waitcnt lgkmcnt(11)
	v_fma_f32 v30, -v16, v244, v23
	v_fma_f32 v30, -v17, v245, v30
	v_fma_f32 v30, -v246, v18, v30
	v_fma_f32 v30, -v247, v19, v30
	ds_read_b128 v[214:217], v5 offset:25440
	s_waitcnt lgkmcnt(11)
	v_fma_f32 v30, -v232, v20, v30
	v_fma_f32 v30, -v233, v21, v30
	v_fma_f32 v30, -v234, v22, v30
	v_fma_f32 v23, -v23, v235, v30
	ds_read_b128 v[228:231], v5 offset:25664
	s_waitcnt lgkmcnt(11)
	v_fma_f32 v24, -v16, v146, v24
	v_fma_f32 v24, -v17, v147, v24
	v_fma_f32 v24, -v18, v148, v24
	v_fma_f32 v24, -v149, v19, v24
	ds_read_b128 v[244:247], v5 offset:25680
	s_waitcnt lgkmcnt(11)
	v_fma_f32 v24, -v150, v20, v24
	v_fma_f32 v24, -v151, v21, v24
	v_fma_f32 v24, -v152, v22, v24
	v_fma_f32 v24, -v153, v23, v24
	ds_read_b128 v[232:235], v5 offset:25696
	s_waitcnt lgkmcnt(11)
	v_fma_f32 v30, -v16, v182, v25
	v_fma_f32 v30, -v17, v183, v30
	v_fma_f32 v30, -v18, v184, v30
	v_fma_f32 v30, -v185, v19, v30
	ds_read_b128 v[146:149], v5 offset:25920
	s_waitcnt lgkmcnt(11)
	v_fma_f32 v30, -v178, v20, v30
	v_fma_f32 v30, -v179, v21, v30
	v_fma_f32 v30, -v180, v22, v30
	v_fma_f32 v30, -v181, v23, v30
	ds_read_b128 v[150:153], v5 offset:25936
	s_waitcnt lgkmcnt(11)
	v_fma_f32 v30, -v186, v24, v30
	v_fma_f32 v25, -v25, v187, v30
	v_fma_f32 v25, -v26, v188, v25
	v_fma_f32 v25, -v27, v189, v25
	ds_read_b128 v[182:185], v5 offset:25952
	s_waitcnt lgkmcnt(11)
	v_fma_f32 v30, -v16, v190, v26
	v_fma_f32 v30, -v17, v191, v30
	v_fma_f32 v30, -v18, v192, v30
	v_fma_f32 v30, -v19, v193, v30
	ds_read_b128 v[178:181], v5 offset:25968
	s_waitcnt lgkmcnt(11)
	v_fma_f32 v30, -v20, v198, v30
	v_fma_f32 v30, -v199, v21, v30
	v_fma_f32 v30, -v200, v22, v30
	v_fma_f32 v30, -v201, v23, v30
	ds_read_b128 v[186:189], v5 offset:26176
	s_waitcnt lgkmcnt(11)
	v_fma_f32 v30, -v194, v24, v30
	v_fma_f32 v30, -v195, v25, v30
	v_fma_f32 v26, -v26, v196, v30
	v_fma_f32 v26, -v27, v197, v26
	ds_read_b128 v[190:193], v5 offset:26192
	s_waitcnt lgkmcnt(11)
	v_fma_f32 v30, -v16, v206, v27
	v_fma_f32 v30, -v17, v207, v30
	v_fma_f32 v30, -v18, v208, v30
	v_fma_f32 v30, -v19, v209, v30
	ds_read_b128 v[198:201], v5 offset:26208
	s_waitcnt lgkmcnt(11)
	v_fma_f32 v30, -v20, v202, v30
	v_fma_f32 v30, -v203, v21, v30
	v_fma_f32 v30, -v204, v22, v30
	v_fma_f32 v30, -v205, v23, v30
	ds_read_b128 v[194:197], v5 offset:26224
	s_waitcnt lgkmcnt(11)
	v_fma_f32 v30, -v214, v24, v30
	v_fma_f32 v30, -v215, v25, v30
	v_fma_f32 v30, -v216, v26, v30
	v_fma_f32 v27, -v27, v217, v30
	ds_read_b128 v[206:209], v5 offset:26432
	s_waitcnt lgkmcnt(11)
	v_fma_f32 v28, -v16, v228, v28
	v_fma_f32 v28, -v17, v229, v28
	v_fma_f32 v28, -v18, v230, v28
	v_fma_f32 v28, -v19, v231, v28
	ds_read_b128 v[202:205], v5 offset:26448
	s_waitcnt lgkmcnt(11)
	v_fma_f32 v28, -v20, v244, v28
	v_fma_f32 v28, -v21, v245, v28
	v_fma_f32 v28, -v246, v22, v28
	v_fma_f32 v28, -v247, v23, v28
	ds_read_b128 v[214:217], v5 offset:26464
	s_waitcnt lgkmcnt(11)
	v_fma_f32 v28, -v232, v24, v28
	v_fma_f32 v28, -v233, v25, v28
	v_fma_f32 v28, -v234, v26, v28
	v_fma_f32 v28, -v235, v27, v28
	ds_read_b128 v[228:231], v5 offset:26480
	s_waitcnt lgkmcnt(11)
	v_fma_f32 v30, -v16, v146, v29
	v_fma_f32 v30, -v17, v147, v30
	v_fma_f32 v30, -v18, v148, v30
	v_fma_f32 v30, -v19, v149, v30
	ds_read_b128 v[244:247], v5 offset:26688
	s_waitcnt lgkmcnt(11)
	v_fma_f32 v30, -v20, v150, v30
	v_fma_f32 v30, -v21, v151, v30
	v_fma_f32 v30, -v22, v152, v30
	v_fma_f32 v30, -v153, v23, v30
	ds_read_b128 v[232:235], v5 offset:26704
	s_waitcnt lgkmcnt(11)
	v_fma_f32 v30, -v182, v24, v30
	v_fma_f32 v30, -v183, v25, v30
	v_fma_f32 v30, -v184, v26, v30
	v_fma_f32 v30, -v185, v27, v30
	ds_read_b128 v[146:149], v5 offset:26720
	s_waitcnt lgkmcnt(11)
	v_fma_f32 v30, -v178, v28, v30
	v_fma_f32 v29, -v29, v179, v30
	v_fma_f32 v29, -v72, v180, v29
	v_fma_f32 v29, -v32, v181, v29
	ds_read_b128 v[150:153], v5 offset:26736
	s_waitcnt lgkmcnt(11)
	v_fma_f32 v30, -v16, v186, v72
	v_fma_f32 v30, -v17, v187, v30
	v_fma_f32 v30, -v18, v188, v30
	v_fma_f32 v30, -v19, v189, v30
	ds_read_b128 v[182:185], v5 offset:26960
	s_waitcnt lgkmcnt(11)
	v_fma_f32 v30, -v20, v190, v30
	v_fma_f32 v30, -v21, v191, v30
	v_fma_f32 v30, -v22, v192, v30
	v_fma_f32 v30, -v23, v193, v30
	ds_read_b128 v[178:181], v5 offset:26944
	s_waitcnt lgkmcnt(11)
	v_fma_f32 v30, -v24, v198, v30
	v_fma_f32 v30, -v199, v25, v30
	v_fma_f32 v30, -v200, v26, v30
	v_fma_f32 v30, -v201, v27, v30
	ds_read_b128 v[186:189], v5 offset:26992
	s_waitcnt lgkmcnt(11)
	v_fma_f32 v30, -v194, v28, v30
	v_fma_f32 v30, -v195, v29, v30
	v_fma_f32 v30, -v72, v196, v30
	v_fma_f32 v30, -v32, v197, v30
	ds_read_b128 v[190:193], v5 offset:26976
	s_waitcnt lgkmcnt(11)
	v_fma_f32 v31, -v16, v206, v32
	v_fma_f32 v31, -v17, v207, v31
	v_fma_f32 v31, -v18, v208, v31
	v_fma_f32 v31, -v19, v209, v31
	ds_read_b128 v[198:201], v5 offset:27200
	s_waitcnt lgkmcnt(11)
	v_fma_f32 v31, -v20, v202, v31
	v_fma_f32 v31, -v21, v203, v31
	v_fma_f32 v31, -v22, v204, v31
	v_fma_f32 v31, -v23, v205, v31
	ds_read_b128 v[194:197], v5 offset:27216
	s_waitcnt lgkmcnt(11)
	v_fma_f32 v31, -v24, v214, v31
	v_fma_f32 v31, -v25, v215, v31
	v_fma_f32 v31, -v216, v26, v31
	v_fma_f32 v31, -v217, v27, v31
	ds_read_b128 v[206:209], v5 offset:27232
	s_waitcnt lgkmcnt(11)
	v_fma_f32 v31, -v228, v28, v31
	v_fma_f32 v31, -v229, v29, v31
	v_fma_f32 v31, -v230, v30, v31
	v_fma_f32 v31, -v32, v231, v31
	ds_read_b128 v[202:205], v5 offset:27248
	s_mov_b64 s[100:101], 0x1000
	v_lshl_add_u64 v[154:155], v[154:155], 0, s[100:101]
	v_readlane_b32 s100, v253, 32
	v_readlane_b32 s101, v253, 33
	s_nop 3
	s_mov_b64 exec, s[100:101]
	v_cvt_pk_bf16_f32 v238, -v16, s0
	global_store_short v[210:211], v238, off offset:2048
	s_not_b64 exec, s[100:101]
	global_store_dword v[154:155], v16, off
	s_mov_b64 exec, -1
	s_waitcnt lgkmcnt(11)
	v_fma_f32 v32, v16, v244, 0
	v_fma_f32 v88, v17, v245, 0
	v_fmac_f32_e32 v32, v18, v246
	v_fmac_f32_e32 v88, v19, v247
	ds_read_b128 v[214:217], v5 offset:27472
	s_waitcnt lgkmcnt(11)
	v_fmac_f32_e32 v32, v20, v232
	v_fmac_f32_e32 v88, v21, v233
	v_fmac_f32_e32 v32, v22, v234
	v_fmac_f32_e32 v88, v23, v235
	ds_read_b128 v[228:231], v5 offset:27456
	s_waitcnt lgkmcnt(11)
	v_fmac_f32_e32 v32, v24, v146
	v_fmac_f32_e32 v88, v25, v147
	v_fmac_f32_e32 v32, v26, v148
	v_fmac_f32_e32 v88, v149, v27
	ds_read_b128 v[244:247], v5 offset:27504
	s_waitcnt lgkmcnt(11)
	v_fmac_f32_e32 v32, v150, v28
	v_fmac_f32_e32 v88, v151, v29
	v_fmac_f32_e32 v32, v152, v30
	v_fmac_f32_e32 v88, v153, v31
	ds_read_b128 v[232:235], v5 offset:27488
	v_add_f32_e32 v32, v32, v88
	v_sub_f32_e32 v32, v33, v32
	s_waitcnt lgkmcnt(10)
	v_fma_f32 v33, v16, v178, 0
	v_fma_f32 v76, v17, v179, 0
	v_fmac_f32_e32 v33, v18, v180
	v_fmac_f32_e32 v76, v19, v181
	ds_read_b128 v[146:149], v5 offset:27712
	v_fmac_f32_e32 v33, v20, v182
	v_fmac_f32_e32 v76, v21, v183
	v_fmac_f32_e32 v33, v22, v184
	v_fmac_f32_e32 v76, v23, v185
	ds_read_b128 v[150:153], v5 offset:27728
	s_waitcnt lgkmcnt(10)
	v_fmac_f32_e32 v33, v24, v190
	v_fmac_f32_e32 v76, v25, v191
	v_fmac_f32_e32 v33, v26, v192
	v_fmac_f32_e32 v76, v27, v193
	ds_read_b128 v[178:181], v5 offset:27744
	v_fmac_f32_e32 v33, v186, v28
	v_fmac_f32_e32 v76, v187, v29
	v_fmac_f32_e32 v33, v188, v30
	v_fmac_f32_e32 v76, v189, v31
	ds_read_b128 v[182:185], v5 offset:27760
	v_add_f32_e32 v33, v33, v76
	v_sub_f32_e32 v33, v34, v33
	s_mov_b64 exec, s[100:101]
	v_cvt_pk_bf16_f32 v238, -v17, s0
	global_store_short v[210:211], v238, off offset:2176
	s_not_b64 exec, s[100:101]
	global_store_dword v[154:155], v17, off offset:256
	s_mov_b64 exec, -1
	s_waitcnt lgkmcnt(11)
	v_fma_f32 v34, v16, v198, 0
	v_fma_f32 v88, v17, v199, 0
	v_fmac_f32_e32 v34, v18, v200
	v_fmac_f32_e32 v88, v19, v201
	ds_read_b128 v[190:193], v5 offset:27984
	s_waitcnt lgkmcnt(11)
	v_fmac_f32_e32 v34, v20, v194
	v_fmac_f32_e32 v88, v21, v195
	v_fmac_f32_e32 v34, v22, v196
	v_fmac_f32_e32 v88, v23, v197
	ds_read_b128 v[186:189], v5 offset:27968
	s_waitcnt lgkmcnt(11)
	v_fmac_f32_e32 v34, v24, v206
	v_fmac_f32_e32 v88, v25, v207
	v_fmac_f32_e32 v34, v26, v208
	v_fmac_f32_e32 v88, v27, v209
	ds_read_b128 v[198:201], v5 offset:28016
	s_waitcnt lgkmcnt(11)
	v_fmac_f32_e32 v34, v28, v202
	v_fmac_f32_e32 v88, v29, v203
	v_fmac_f32_e32 v34, v204, v30
	v_fmac_f32_e32 v88, v205, v31
	ds_read_b128 v[194:197], v5 offset:28000
	v_add_f32_e32 v34, v34, v88
	v_sub_f32_e32 v34, v35, v34
	s_waitcnt lgkmcnt(10)
	v_fma_f32 v35, v16, v228, 0
	v_fma_f32 v76, v17, v229, 0
	v_fmac_f32_e32 v35, v18, v230
	v_fmac_f32_e32 v76, v19, v231
	ds_read_b128 v[206:209], v5 offset:28224
	v_fmac_f32_e32 v35, v20, v214
	v_fmac_f32_e32 v76, v21, v215
	v_fmac_f32_e32 v35, v22, v216
	v_fmac_f32_e32 v76, v23, v217
	ds_read_b128 v[202:205], v5 offset:28240
	s_waitcnt lgkmcnt(10)
	v_fmac_f32_e32 v35, v24, v232
	v_fmac_f32_e32 v76, v25, v233
	v_fmac_f32_e32 v35, v26, v234
	v_fmac_f32_e32 v76, v27, v235
	ds_read_b128 v[228:231], v5 offset:28256
	v_fmac_f32_e32 v35, v28, v244
	v_fmac_f32_e32 v76, v29, v245
	v_fmac_f32_e32 v35, v246, v30
	v_fmac_f32_e32 v76, v247, v31
	ds_read_b128 v[214:217], v5 offset:28272
	v_add_f32_e32 v35, v35, v76
	v_sub_f32_e32 v35, v36, v35
	s_mov_b64 exec, s[100:101]
	v_cvt_pk_bf16_f32 v238, -v18, s0
	global_store_short v[210:211], v238, off offset:2304
	s_not_b64 exec, s[100:101]
	global_store_dword v[154:155], v18, off offset:512
	s_mov_b64 exec, -1
	s_waitcnt lgkmcnt(11)
	v_fma_f32 v36, v16, v146, 0
	v_fma_f32 v88, v17, v147, 0
	v_fmac_f32_e32 v36, v18, v148
	v_fmac_f32_e32 v88, v19, v149
	ds_read_b128 v[232:235], v5 offset:28496
	s_waitcnt lgkmcnt(11)
	v_fmac_f32_e32 v36, v20, v150
	v_fmac_f32_e32 v88, v21, v151
	v_fmac_f32_e32 v36, v22, v152
	v_fmac_f32_e32 v88, v23, v153
	ds_read_b128 v[244:247], v5 offset:28480
	s_waitcnt lgkmcnt(11)
	v_fmac_f32_e32 v36, v24, v178
	v_fmac_f32_e32 v88, v25, v179
	v_fmac_f32_e32 v36, v26, v180
	v_fmac_f32_e32 v88, v27, v181
	ds_read_b128 v[146:149], v5 offset:28528
	s_waitcnt lgkmcnt(11)
	v_fmac_f32_e32 v36, v28, v182
	v_fmac_f32_e32 v88, v29, v183
	v_fmac_f32_e32 v36, v30, v184
	v_fmac_f32_e32 v88, v31, v185
	ds_read_b128 v[150:153], v5 offset:28512
	v_add_f32_e32 v36, v36, v88
	v_sub_f32_e32 v36, v37, v36
	s_waitcnt lgkmcnt(10)
	v_fma_f32 v37, v16, v186, 0
	v_fma_f32 v76, v17, v187, 0
	v_fmac_f32_e32 v37, v18, v188
	v_fmac_f32_e32 v76, v19, v189
	ds_read_b128 v[178:181], v5 offset:28736
	v_fmac_f32_e32 v37, v20, v190
	v_fmac_f32_e32 v76, v21, v191
	v_fmac_f32_e32 v37, v22, v192
	v_fmac_f32_e32 v76, v23, v193
	ds_read_b128 v[182:185], v5 offset:28752
	s_waitcnt lgkmcnt(10)
	v_fmac_f32_e32 v37, v24, v194
	v_fmac_f32_e32 v76, v25, v195
	v_fmac_f32_e32 v37, v26, v196
	v_fmac_f32_e32 v76, v27, v197
	ds_read_b128 v[186:189], v5 offset:28768
	v_fmac_f32_e32 v37, v28, v198
	v_fmac_f32_e32 v76, v29, v199
	v_fmac_f32_e32 v37, v30, v200
	v_fmac_f32_e32 v76, v31, v201
	ds_read_b128 v[190:193], v5 offset:28784
	v_add_f32_e32 v37, v37, v76
	v_sub_f32_e32 v37, v38, v37
	s_mov_b64 exec, s[100:101]
	v_cvt_pk_bf16_f32 v238, -v19, s0
	global_store_short v[210:211], v238, off offset:2432
	s_not_b64 exec, s[100:101]
	global_store_dword v[154:155], v19, off offset:768
	s_mov_b64 exec, -1
	s_waitcnt lgkmcnt(11)
	v_fma_f32 v38, v16, v206, 0
	v_fma_f32 v88, v17, v207, 0
	v_fmac_f32_e32 v38, v18, v208
	v_fmac_f32_e32 v88, v19, v209
	ds_read_b128 v[194:197], v5 offset:29008
	s_waitcnt lgkmcnt(11)
	v_fmac_f32_e32 v38, v20, v202
	v_fmac_f32_e32 v88, v21, v203
	v_fmac_f32_e32 v38, v22, v204
	v_fmac_f32_e32 v88, v23, v205
	ds_read_b128 v[198:201], v5 offset:28992
	s_waitcnt lgkmcnt(11)
	v_fmac_f32_e32 v38, v24, v228
	v_fmac_f32_e32 v88, v25, v229
	v_fmac_f32_e32 v38, v26, v230
	v_fmac_f32_e32 v88, v27, v231
	ds_read_b128 v[206:209], v5 offset:29040
	s_waitcnt lgkmcnt(11)
	v_fmac_f32_e32 v38, v28, v214
	v_fmac_f32_e32 v88, v29, v215
	v_fmac_f32_e32 v38, v30, v216
	v_fmac_f32_e32 v88, v31, v217
	ds_read_b128 v[202:205], v5 offset:29024
	v_add_f32_e32 v38, v38, v88
	v_sub_f32_e32 v38, v39, v38
	s_waitcnt lgkmcnt(10)
	v_fma_f32 v39, v16, v244, 0
	v_fma_f32 v76, v17, v245, 0
	v_fmac_f32_e32 v39, v18, v246
	v_fmac_f32_e32 v76, v19, v247
	ds_read_b128 v[228:231], v5 offset:29248
	v_fmac_f32_e32 v39, v20, v232
	v_fmac_f32_e32 v76, v21, v233
	v_fmac_f32_e32 v39, v22, v234
	v_fmac_f32_e32 v76, v23, v235
	ds_read_b128 v[214:217], v5 offset:29264
	s_waitcnt lgkmcnt(10)
	v_fmac_f32_e32 v39, v24, v150
	v_fmac_f32_e32 v76, v25, v151
	v_fmac_f32_e32 v39, v26, v152
	v_fmac_f32_e32 v76, v27, v153
	ds_read_b128 v[244:247], v5 offset:29280
	v_fmac_f32_e32 v39, v28, v146
	v_fmac_f32_e32 v76, v29, v147
	v_fmac_f32_e32 v39, v30, v148
	v_fmac_f32_e32 v76, v31, v149
	ds_read_b128 v[232:235], v5 offset:29296
	v_add_f32_e32 v39, v39, v76
	v_sub_f32_e32 v39, v40, v39
	s_mov_b64 exec, s[100:101]
	v_cvt_pk_bf16_f32 v238, -v20, s0
	global_store_short v[210:211], v238, off offset:2560
	s_not_b64 exec, s[100:101]
	global_store_dword v[154:155], v20, off offset:1024
	s_mov_b64 exec, -1
	s_waitcnt lgkmcnt(11)
	v_fma_f32 v40, v16, v178, 0
	v_fma_f32 v88, v17, v179, 0
	v_fmac_f32_e32 v40, v18, v180
	v_fmac_f32_e32 v88, v19, v181
	ds_read_b128 v[150:153], v5 offset:29520
	s_waitcnt lgkmcnt(11)
	v_fmac_f32_e32 v40, v20, v182
	v_fmac_f32_e32 v88, v21, v183
	v_fmac_f32_e32 v40, v22, v184
	v_fmac_f32_e32 v88, v23, v185
	ds_read_b128 v[146:149], v5 offset:29504
	s_waitcnt lgkmcnt(11)
	v_fmac_f32_e32 v40, v24, v186
	v_fmac_f32_e32 v88, v25, v187
	v_fmac_f32_e32 v40, v26, v188
	v_fmac_f32_e32 v88, v27, v189
	ds_read_b128 v[178:181], v5 offset:29552
	s_waitcnt lgkmcnt(11)
	v_fmac_f32_e32 v40, v28, v190
	v_fmac_f32_e32 v88, v29, v191
	v_fmac_f32_e32 v40, v30, v192
	v_fmac_f32_e32 v88, v31, v193
	ds_read_b128 v[182:185], v5 offset:29536
	v_add_f32_e32 v40, v40, v88
	v_sub_f32_e32 v40, v41, v40
	s_waitcnt lgkmcnt(10)
	v_fma_f32 v41, v16, v198, 0
	v_fma_f32 v76, v17, v199, 0
	v_fmac_f32_e32 v41, v18, v200
	v_fmac_f32_e32 v76, v19, v201
	ds_read_b128 v[186:189], v5 offset:29760
	v_fmac_f32_e32 v41, v20, v194
	v_fmac_f32_e32 v76, v21, v195
	v_fmac_f32_e32 v41, v22, v196
	v_fmac_f32_e32 v76, v23, v197
	ds_read_b128 v[190:193], v5 offset:29776
	s_waitcnt lgkmcnt(10)
	v_fmac_f32_e32 v41, v24, v202
	v_fmac_f32_e32 v76, v25, v203
	v_fmac_f32_e32 v41, v26, v204
	v_fmac_f32_e32 v76, v27, v205
	ds_read_b128 v[198:201], v5 offset:29792
	v_fmac_f32_e32 v41, v28, v206
	v_fmac_f32_e32 v76, v29, v207
	v_fmac_f32_e32 v41, v30, v208
	v_fmac_f32_e32 v76, v31, v209
	ds_read_b128 v[194:197], v5 offset:29808
	v_add_f32_e32 v41, v41, v76
	v_sub_f32_e32 v41, v42, v41
	s_mov_b64 exec, s[100:101]
	v_cvt_pk_bf16_f32 v238, -v21, s0
	global_store_short v[210:211], v238, off offset:2688
	s_not_b64 exec, s[100:101]
	global_store_dword v[154:155], v21, off offset:1280
	s_mov_b64 exec, -1
	s_waitcnt lgkmcnt(11)
	v_fma_f32 v42, v16, v228, 0
	v_fma_f32 v88, v17, v229, 0
	v_fmac_f32_e32 v42, v18, v230
	v_fmac_f32_e32 v88, v19, v231
	ds_read_b128 v[202:205], v5 offset:30032
	s_waitcnt lgkmcnt(11)
	v_fmac_f32_e32 v42, v20, v214
	v_fmac_f32_e32 v88, v21, v215
	v_fmac_f32_e32 v42, v22, v216
	v_fmac_f32_e32 v88, v23, v217
	ds_read_b128 v[206:209], v5 offset:30016
	s_waitcnt lgkmcnt(11)
	v_fmac_f32_e32 v42, v24, v244
	v_fmac_f32_e32 v88, v25, v245
	v_fmac_f32_e32 v42, v26, v246
	v_fmac_f32_e32 v88, v27, v247
	ds_read_b128 v[228:231], v5 offset:30064
	s_waitcnt lgkmcnt(11)
	v_fmac_f32_e32 v42, v28, v232
	v_fmac_f32_e32 v88, v29, v233
	v_fmac_f32_e32 v42, v30, v234
	v_fmac_f32_e32 v88, v31, v235
	ds_read_b128 v[214:217], v5 offset:30048
	v_add_f32_e32 v42, v42, v88
	v_sub_f32_e32 v42, v43, v42
	s_waitcnt lgkmcnt(10)
	v_fma_f32 v43, v16, v146, 0
	v_fma_f32 v76, v17, v147, 0
	v_fmac_f32_e32 v43, v18, v148
	v_fmac_f32_e32 v76, v19, v149
	ds_read_b128 v[244:247], v5 offset:30272
	v_fmac_f32_e32 v43, v20, v150
	v_fmac_f32_e32 v76, v21, v151
	v_fmac_f32_e32 v43, v22, v152
	v_fmac_f32_e32 v76, v23, v153
	ds_read_b128 v[232:235], v5 offset:30288
	s_waitcnt lgkmcnt(10)
	v_fmac_f32_e32 v43, v24, v182
	v_fmac_f32_e32 v76, v25, v183
	v_fmac_f32_e32 v43, v26, v184
	v_fmac_f32_e32 v76, v27, v185
	ds_read_b128 v[146:149], v5 offset:30304
	v_fmac_f32_e32 v43, v28, v178
	v_fmac_f32_e32 v76, v29, v179
	v_fmac_f32_e32 v43, v30, v180
	v_fmac_f32_e32 v76, v31, v181
	ds_read_b128 v[150:153], v5 offset:30320
	v_add_f32_e32 v43, v43, v76
	v_sub_f32_e32 v43, v44, v43
	s_mov_b64 exec, s[100:101]
	v_cvt_pk_bf16_f32 v238, -v22, s0
	global_store_short v[210:211], v238, off offset:2816
	s_not_b64 exec, s[100:101]
	global_store_dword v[154:155], v22, off offset:1536
	s_mov_b64 exec, -1
	s_waitcnt lgkmcnt(11)
	v_fma_f32 v44, v16, v186, 0
	v_fma_f32 v88, v17, v187, 0
	v_fmac_f32_e32 v44, v18, v188
	v_fmac_f32_e32 v88, v19, v189
	ds_read_b128 v[182:185], v5 offset:30544
	s_waitcnt lgkmcnt(11)
	v_fmac_f32_e32 v44, v20, v190
	v_fmac_f32_e32 v88, v21, v191
	v_fmac_f32_e32 v44, v22, v192
	v_fmac_f32_e32 v88, v23, v193
	ds_read_b128 v[178:181], v5 offset:30528
	s_waitcnt lgkmcnt(11)
	v_fmac_f32_e32 v44, v24, v198
	v_fmac_f32_e32 v88, v25, v199
	v_fmac_f32_e32 v44, v26, v200
	v_fmac_f32_e32 v88, v27, v201
	ds_read_b128 v[186:189], v5 offset:30576
	s_waitcnt lgkmcnt(11)
	v_fmac_f32_e32 v44, v28, v194
	v_fmac_f32_e32 v88, v29, v195
	v_fmac_f32_e32 v44, v30, v196
	v_fmac_f32_e32 v88, v31, v197
	ds_read_b128 v[190:193], v5 offset:30560
	v_add_f32_e32 v44, v44, v88
	v_sub_f32_e32 v44, v45, v44
	s_waitcnt lgkmcnt(10)
	v_fma_f32 v45, v16, v206, 0
	v_fma_f32 v76, v17, v207, 0
	v_fmac_f32_e32 v45, v18, v208
	v_fmac_f32_e32 v76, v19, v209
	ds_read_b128 v[198:201], v5 offset:30784
	v_fmac_f32_e32 v45, v20, v202
	v_fmac_f32_e32 v76, v21, v203
	v_fmac_f32_e32 v45, v22, v204
	v_fmac_f32_e32 v76, v23, v205
	ds_read_b128 v[194:197], v5 offset:30800
	s_waitcnt lgkmcnt(10)
	v_fmac_f32_e32 v45, v24, v214
	v_fmac_f32_e32 v76, v25, v215
	v_fmac_f32_e32 v45, v26, v216
	v_fmac_f32_e32 v76, v27, v217
	ds_read_b128 v[206:209], v5 offset:30816
	v_fmac_f32_e32 v45, v28, v228
	v_fmac_f32_e32 v76, v29, v229
	v_fmac_f32_e32 v45, v30, v230
	v_fmac_f32_e32 v76, v31, v231
	ds_read_b128 v[202:205], v5 offset:30832
	v_add_f32_e32 v45, v45, v76
	v_sub_f32_e32 v45, v46, v45
	s_mov_b64 exec, s[100:101]
	v_cvt_pk_bf16_f32 v238, -v23, s0
	global_store_short v[210:211], v238, off offset:2944
	s_not_b64 exec, s[100:101]
	global_store_dword v[154:155], v23, off offset:1792
	s_mov_b64 exec, -1
	s_waitcnt lgkmcnt(11)
	v_fma_f32 v46, v16, v244, 0
	v_fma_f32 v88, v17, v245, 0
	v_fmac_f32_e32 v46, v18, v246
	v_fmac_f32_e32 v88, v19, v247
	ds_read_b128 v[214:217], v5 offset:31056
	s_waitcnt lgkmcnt(11)
	v_fmac_f32_e32 v46, v20, v232
	v_fmac_f32_e32 v88, v21, v233
	v_fmac_f32_e32 v46, v22, v234
	v_fmac_f32_e32 v88, v23, v235
	ds_read_b128 v[228:231], v5 offset:31040
	s_waitcnt lgkmcnt(11)
	v_fmac_f32_e32 v46, v24, v146
	v_fmac_f32_e32 v88, v25, v147
	v_fmac_f32_e32 v46, v26, v148
	v_fmac_f32_e32 v88, v27, v149
	ds_read_b128 v[244:247], v5 offset:31088
	s_waitcnt lgkmcnt(11)
	v_fmac_f32_e32 v46, v28, v150
	v_fmac_f32_e32 v88, v29, v151
	v_fmac_f32_e32 v46, v30, v152
	v_fmac_f32_e32 v88, v31, v153
	ds_read_b128 v[232:235], v5 offset:31072
	v_add_f32_e32 v46, v46, v88
	v_sub_f32_e32 v46, v47, v46
	s_waitcnt lgkmcnt(10)
	v_fma_f32 v47, v16, v178, 0
	v_fma_f32 v76, v17, v179, 0
	v_fmac_f32_e32 v47, v18, v180
	v_fmac_f32_e32 v76, v19, v181
	ds_read_b128 v[146:149], v5 offset:31296
	v_fmac_f32_e32 v47, v20, v182
	v_fmac_f32_e32 v76, v21, v183
	v_fmac_f32_e32 v47, v22, v184
	v_fmac_f32_e32 v76, v23, v185
	ds_read_b128 v[150:153], v5 offset:31312
	s_waitcnt lgkmcnt(10)
	v_fmac_f32_e32 v47, v24, v190
	v_fmac_f32_e32 v76, v25, v191
	v_fmac_f32_e32 v47, v26, v192
	v_fmac_f32_e32 v76, v27, v193
	ds_read_b128 v[178:181], v5 offset:31328
	v_fmac_f32_e32 v47, v28, v186
	v_fmac_f32_e32 v76, v29, v187
	v_fmac_f32_e32 v47, v30, v188
	v_fmac_f32_e32 v76, v31, v189
	ds_read_b128 v[182:185], v5 offset:31344
	v_add_f32_e32 v47, v47, v76
	v_sub_f32_e32 v47, v48, v47
	s_mov_b64 exec, s[100:101]
	v_cvt_pk_bf16_f32 v238, -v24, s0
	global_store_short v[210:211], v238, off offset:3072
	s_not_b64 exec, s[100:101]
	global_store_dword v[154:155], v24, off offset:2048
	s_mov_b64 exec, -1
	s_waitcnt lgkmcnt(11)
	v_fma_f32 v48, v16, v198, 0
	v_fma_f32 v88, v17, v199, 0
	v_fmac_f32_e32 v48, v18, v200
	v_fmac_f32_e32 v88, v19, v201
	ds_read_b128 v[190:193], v5 offset:31568
	s_waitcnt lgkmcnt(11)
	v_fmac_f32_e32 v48, v20, v194
	v_fmac_f32_e32 v88, v21, v195
	v_fmac_f32_e32 v48, v22, v196
	v_fmac_f32_e32 v88, v23, v197
	ds_read_b128 v[186:189], v5 offset:31552
	s_waitcnt lgkmcnt(11)
	v_fmac_f32_e32 v48, v24, v206
	v_fmac_f32_e32 v88, v25, v207
	v_fmac_f32_e32 v48, v26, v208
	v_fmac_f32_e32 v88, v27, v209
	ds_read_b128 v[198:201], v5 offset:31600
	s_waitcnt lgkmcnt(11)
	v_fmac_f32_e32 v48, v28, v202
	v_fmac_f32_e32 v88, v29, v203
	v_fmac_f32_e32 v48, v30, v204
	v_fmac_f32_e32 v88, v31, v205
	ds_read_b128 v[194:197], v5 offset:31584
	v_add_f32_e32 v48, v48, v88
	v_sub_f32_e32 v48, v49, v48
	s_waitcnt lgkmcnt(10)
	v_fma_f32 v49, v16, v228, 0
	v_fma_f32 v76, v17, v229, 0
	v_fmac_f32_e32 v49, v18, v230
	v_fmac_f32_e32 v76, v19, v231
	ds_read_b128 v[206:209], v5 offset:31808
	v_fmac_f32_e32 v49, v20, v214
	v_fmac_f32_e32 v76, v21, v215
	v_fmac_f32_e32 v49, v22, v216
	v_fmac_f32_e32 v76, v23, v217
	ds_read_b128 v[202:205], v5 offset:31824
	s_waitcnt lgkmcnt(10)
	v_fmac_f32_e32 v49, v24, v232
	v_fmac_f32_e32 v76, v25, v233
	v_fmac_f32_e32 v49, v26, v234
	v_fmac_f32_e32 v76, v27, v235
	ds_read_b128 v[228:231], v5 offset:31840
	v_fmac_f32_e32 v49, v28, v244
	v_fmac_f32_e32 v76, v29, v245
	v_fmac_f32_e32 v49, v30, v246
	v_fmac_f32_e32 v76, v31, v247
	ds_read_b128 v[214:217], v5 offset:31856
	v_add_f32_e32 v49, v49, v76
	v_sub_f32_e32 v49, v50, v49
	s_mov_b64 exec, s[100:101]
	v_cvt_pk_bf16_f32 v238, -v25, s0
	global_store_short v[210:211], v238, off offset:3200
	s_not_b64 exec, s[100:101]
	global_store_dword v[154:155], v25, off offset:2304
	s_mov_b64 exec, -1
	s_waitcnt lgkmcnt(11)
	v_fma_f32 v50, v16, v146, 0
	v_fma_f32 v88, v17, v147, 0
	v_fmac_f32_e32 v50, v18, v148
	v_fmac_f32_e32 v88, v19, v149
	ds_read_b128 v[232:235], v5 offset:32080
	s_waitcnt lgkmcnt(11)
	v_fmac_f32_e32 v50, v20, v150
	v_fmac_f32_e32 v88, v21, v151
	v_fmac_f32_e32 v50, v22, v152
	v_fmac_f32_e32 v88, v23, v153
	ds_read_b128 v[244:247], v5 offset:32064
	s_waitcnt lgkmcnt(11)
	v_fmac_f32_e32 v50, v24, v178
	v_fmac_f32_e32 v88, v25, v179
	v_fmac_f32_e32 v50, v26, v180
	v_fmac_f32_e32 v88, v27, v181
	ds_read_b128 v[146:149], v5 offset:32112
	s_waitcnt lgkmcnt(11)
	v_fmac_f32_e32 v50, v28, v182
	v_fmac_f32_e32 v88, v29, v183
	v_fmac_f32_e32 v50, v30, v184
	v_fmac_f32_e32 v88, v31, v185
	ds_read_b128 v[150:153], v5 offset:32096
	v_add_f32_e32 v50, v50, v88
	v_sub_f32_e32 v50, v51, v50
	s_waitcnt lgkmcnt(10)
	v_fma_f32 v51, v16, v186, 0
	v_fma_f32 v76, v17, v187, 0
	v_fmac_f32_e32 v51, v18, v188
	v_fmac_f32_e32 v76, v19, v189
	ds_read_b128 v[178:181], v5 offset:32320
	v_fmac_f32_e32 v51, v20, v190
	v_fmac_f32_e32 v76, v21, v191
	v_fmac_f32_e32 v51, v22, v192
	v_fmac_f32_e32 v76, v23, v193
	ds_read_b128 v[182:185], v5 offset:32336
	s_waitcnt lgkmcnt(10)
	v_fmac_f32_e32 v51, v24, v194
	v_fmac_f32_e32 v76, v25, v195
	v_fmac_f32_e32 v51, v26, v196
	v_fmac_f32_e32 v76, v27, v197
	ds_read_b128 v[186:189], v5 offset:32352
	v_fmac_f32_e32 v51, v28, v198
	v_fmac_f32_e32 v76, v29, v199
	v_fmac_f32_e32 v51, v30, v200
	v_fmac_f32_e32 v76, v31, v201
	ds_read_b128 v[190:193], v5 offset:32368
	v_add_f32_e32 v51, v51, v76
	v_sub_f32_e32 v51, v52, v51
	s_mov_b64 exec, s[100:101]
	v_cvt_pk_bf16_f32 v238, -v26, s0
	global_store_short v[210:211], v238, off offset:3328
	s_not_b64 exec, s[100:101]
	global_store_dword v[154:155], v26, off offset:2560
	s_mov_b64 exec, -1
	s_waitcnt lgkmcnt(11)
	v_fma_f32 v52, v16, v206, 0
	v_fma_f32 v88, v17, v207, 0
	v_fmac_f32_e32 v52, v18, v208
	v_fmac_f32_e32 v88, v19, v209
	ds_read_b128 v[194:197], v5 offset:32592
	s_waitcnt lgkmcnt(11)
	v_fmac_f32_e32 v52, v20, v202
	v_fmac_f32_e32 v88, v21, v203
	v_fmac_f32_e32 v52, v22, v204
	v_fmac_f32_e32 v88, v23, v205
	ds_read_b128 v[198:201], v5 offset:32576
	s_waitcnt lgkmcnt(11)
	v_fmac_f32_e32 v52, v24, v228
	v_fmac_f32_e32 v88, v25, v229
	v_fmac_f32_e32 v52, v26, v230
	v_fmac_f32_e32 v88, v27, v231
	ds_read_b128 v[206:209], v5 offset:32624
	s_waitcnt lgkmcnt(11)
	v_fmac_f32_e32 v52, v28, v214
	v_fmac_f32_e32 v88, v29, v215
	v_fmac_f32_e32 v52, v30, v216
	v_fmac_f32_e32 v88, v31, v217
	ds_read_b128 v[202:205], v5 offset:32608
	v_add_f32_e32 v52, v52, v88
	v_sub_f32_e32 v52, v53, v52
	s_waitcnt lgkmcnt(10)
	v_fma_f32 v53, v16, v244, 0
	v_fma_f32 v76, v17, v245, 0
	v_fmac_f32_e32 v53, v18, v246
	v_fmac_f32_e32 v76, v19, v247
	ds_read_b128 v[228:231], v5 offset:32832
	v_fmac_f32_e32 v53, v20, v232
	v_fmac_f32_e32 v76, v21, v233
	v_fmac_f32_e32 v53, v22, v234
	v_fmac_f32_e32 v76, v23, v235
	ds_read_b128 v[214:217], v5 offset:32848
	s_waitcnt lgkmcnt(10)
	v_fmac_f32_e32 v53, v24, v150
	v_fmac_f32_e32 v76, v25, v151
	v_fmac_f32_e32 v53, v26, v152
	v_fmac_f32_e32 v76, v27, v153
	ds_read_b128 v[244:247], v5 offset:32864
	v_fmac_f32_e32 v53, v28, v146
	v_fmac_f32_e32 v76, v29, v147
	v_fmac_f32_e32 v53, v30, v148
	v_fmac_f32_e32 v76, v31, v149
	ds_read_b128 v[232:235], v5 offset:32880
	v_add_f32_e32 v53, v53, v76
	v_sub_f32_e32 v53, v54, v53
	s_mov_b64 exec, s[100:101]
	v_cvt_pk_bf16_f32 v238, -v27, s0
	global_store_short v[210:211], v238, off offset:3456
	s_not_b64 exec, s[100:101]
	global_store_dword v[154:155], v27, off offset:2816
	s_mov_b64 exec, -1
	s_waitcnt lgkmcnt(11)
	v_fma_f32 v54, v16, v178, 0
	v_fma_f32 v88, v17, v179, 0
	v_fmac_f32_e32 v54, v18, v180
	v_fmac_f32_e32 v88, v19, v181
	ds_read_b128 v[150:153], v5 offset:33104
	s_waitcnt lgkmcnt(11)
	v_fmac_f32_e32 v54, v20, v182
	v_fmac_f32_e32 v88, v21, v183
	v_fmac_f32_e32 v54, v22, v184
	v_fmac_f32_e32 v88, v23, v185
	ds_read_b128 v[146:149], v5 offset:33088
	s_waitcnt lgkmcnt(11)
	v_fmac_f32_e32 v54, v24, v186
	v_fmac_f32_e32 v88, v25, v187
	v_fmac_f32_e32 v54, v26, v188
	v_fmac_f32_e32 v88, v27, v189
	ds_read_b128 v[178:181], v5 offset:33136
	s_waitcnt lgkmcnt(11)
	v_fmac_f32_e32 v54, v28, v190
	v_fmac_f32_e32 v88, v29, v191
	v_fmac_f32_e32 v54, v30, v192
	v_fmac_f32_e32 v88, v31, v193
	ds_read_b128 v[182:185], v5 offset:33120
	v_add_f32_e32 v54, v54, v88
	v_sub_f32_e32 v54, v55, v54
	s_waitcnt lgkmcnt(10)
	v_fma_f32 v55, v16, v198, 0
	v_fma_f32 v76, v17, v199, 0
	v_fmac_f32_e32 v55, v18, v200
	v_fmac_f32_e32 v76, v19, v201
	ds_read_b128 v[186:189], v5 offset:33344
	v_fmac_f32_e32 v55, v20, v194
	v_fmac_f32_e32 v76, v21, v195
	v_fmac_f32_e32 v55, v22, v196
	v_fmac_f32_e32 v76, v23, v197
	ds_read_b128 v[190:193], v5 offset:33360
	s_waitcnt lgkmcnt(10)
	v_fmac_f32_e32 v55, v24, v202
	v_fmac_f32_e32 v76, v25, v203
	v_fmac_f32_e32 v55, v26, v204
	v_fmac_f32_e32 v76, v27, v205
	ds_read_b128 v[198:201], v5 offset:33376
	v_fmac_f32_e32 v55, v28, v206
	v_fmac_f32_e32 v76, v29, v207
	v_fmac_f32_e32 v55, v30, v208
	v_fmac_f32_e32 v76, v31, v209
	ds_read_b128 v[194:197], v5 offset:33392
	v_add_f32_e32 v55, v55, v76
	v_sub_f32_e32 v55, v56, v55
	s_mov_b64 exec, s[100:101]
	v_cvt_pk_bf16_f32 v238, -v28, s0
	global_store_short v[210:211], v238, off offset:3584
	s_not_b64 exec, s[100:101]
	global_store_dword v[154:155], v28, off offset:3072
	s_mov_b64 exec, -1
	s_waitcnt lgkmcnt(11)
	v_fma_f32 v56, v16, v228, 0
	v_fma_f32 v88, v17, v229, 0
	v_fmac_f32_e32 v56, v18, v230
	v_fmac_f32_e32 v88, v19, v231
	ds_read_b128 v[202:205], v5 offset:33616
	s_waitcnt lgkmcnt(11)
	v_fmac_f32_e32 v56, v20, v214
	v_fmac_f32_e32 v88, v21, v215
	v_fmac_f32_e32 v56, v22, v216
	v_fmac_f32_e32 v88, v23, v217
	ds_read_b128 v[206:209], v5 offset:33600
	s_waitcnt lgkmcnt(11)
	v_fmac_f32_e32 v56, v24, v244
	v_fmac_f32_e32 v88, v25, v245
	v_fmac_f32_e32 v56, v26, v246
	v_fmac_f32_e32 v88, v27, v247
	ds_read_b128 v[228:231], v5 offset:33648
	s_waitcnt lgkmcnt(11)
	v_fmac_f32_e32 v56, v28, v232
	v_fmac_f32_e32 v88, v29, v233
	v_fmac_f32_e32 v56, v30, v234
	v_fmac_f32_e32 v88, v31, v235
	ds_read_b128 v[214:217], v5 offset:33632
	v_add_f32_e32 v56, v56, v88
	v_sub_f32_e32 v56, v57, v56
	s_waitcnt lgkmcnt(10)
	v_fma_f32 v57, v16, v146, 0
	v_fma_f32 v76, v17, v147, 0
	v_fmac_f32_e32 v57, v18, v148
	v_fmac_f32_e32 v76, v19, v149
	ds_read_b128 v[244:247], v5 offset:33856
	v_fmac_f32_e32 v57, v20, v150
	v_fmac_f32_e32 v76, v21, v151
	v_fmac_f32_e32 v57, v22, v152
	v_fmac_f32_e32 v76, v23, v153
	ds_read_b128 v[232:235], v5 offset:33872
	s_waitcnt lgkmcnt(10)
	v_fmac_f32_e32 v57, v24, v182
	v_fmac_f32_e32 v76, v25, v183
	v_fmac_f32_e32 v57, v26, v184
	v_fmac_f32_e32 v76, v27, v185
	ds_read_b128 v[146:149], v5 offset:33888
	v_fmac_f32_e32 v57, v28, v178
	v_fmac_f32_e32 v76, v29, v179
	v_fmac_f32_e32 v57, v30, v180
	v_fmac_f32_e32 v76, v31, v181
	ds_read_b128 v[150:153], v5 offset:33904
	v_add_f32_e32 v57, v57, v76
	v_sub_f32_e32 v57, v58, v57
	s_mov_b64 exec, s[100:101]
	v_cvt_pk_bf16_f32 v238, -v29, s0
	global_store_short v[210:211], v238, off offset:3712
	s_not_b64 exec, s[100:101]
	global_store_dword v[154:155], v29, off offset:3328
	s_mov_b64 exec, -1
	s_waitcnt lgkmcnt(11)
	v_fma_f32 v58, v16, v186, 0
	v_fma_f32 v88, v17, v187, 0
	v_fmac_f32_e32 v58, v18, v188
	v_fmac_f32_e32 v88, v19, v189
	ds_read_b128 v[182:185], v5 offset:34128
	s_waitcnt lgkmcnt(11)
	v_fmac_f32_e32 v58, v20, v190
	v_fmac_f32_e32 v88, v21, v191
	v_fmac_f32_e32 v58, v22, v192
	v_fmac_f32_e32 v88, v23, v193
	ds_read_b128 v[178:181], v5 offset:34112
	s_waitcnt lgkmcnt(11)
	v_fmac_f32_e32 v58, v24, v198
	v_fmac_f32_e32 v88, v25, v199
	v_fmac_f32_e32 v58, v26, v200
	v_fmac_f32_e32 v88, v27, v201
	ds_read_b128 v[186:189], v5 offset:34160
	s_waitcnt lgkmcnt(11)
	v_fmac_f32_e32 v58, v28, v194
	v_fmac_f32_e32 v88, v29, v195
	v_fmac_f32_e32 v58, v30, v196
	v_fmac_f32_e32 v88, v31, v197
	ds_read_b128 v[190:193], v5 offset:34144
	v_add_f32_e32 v58, v58, v88
	v_sub_f32_e32 v58, v59, v58
	s_waitcnt lgkmcnt(10)
	v_fma_f32 v59, v16, v206, 0
	v_fma_f32 v76, v17, v207, 0
	v_fmac_f32_e32 v59, v18, v208
	v_fmac_f32_e32 v76, v19, v209
	ds_read_b128 v[198:201], v5 offset:34368
	v_fmac_f32_e32 v59, v20, v202
	v_fmac_f32_e32 v76, v21, v203
	v_fmac_f32_e32 v59, v22, v204
	v_fmac_f32_e32 v76, v23, v205
	ds_read_b128 v[194:197], v5 offset:34384
	s_waitcnt lgkmcnt(10)
	v_fmac_f32_e32 v59, v24, v214
	v_fmac_f32_e32 v76, v25, v215
	v_fmac_f32_e32 v59, v26, v216
	v_fmac_f32_e32 v76, v27, v217
	ds_read_b128 v[206:209], v5 offset:34400
	v_fmac_f32_e32 v59, v28, v228
	v_fmac_f32_e32 v76, v29, v229
	v_fmac_f32_e32 v59, v30, v230
	v_fmac_f32_e32 v76, v31, v231
	ds_read_b128 v[202:205], v5 offset:34416
	v_add_f32_e32 v59, v59, v76
	v_sub_f32_e32 v59, v61, v59
	s_mov_b64 exec, s[100:101]
	v_cvt_pk_bf16_f32 v238, -v30, s0
	global_store_short v[210:211], v238, off offset:3840
	s_not_b64 exec, s[100:101]
	global_store_dword v[154:155], v30, off offset:3584
	s_mov_b64 exec, -1
	s_waitcnt lgkmcnt(11)
	v_fma_f32 v61, v16, v244, 0
	v_fma_f32 v88, v17, v245, 0
	v_fmac_f32_e32 v61, v18, v246
	v_fmac_f32_e32 v88, v19, v247
	ds_read_b128 v[214:217], v5 offset:34640
	s_waitcnt lgkmcnt(11)
	v_fmac_f32_e32 v61, v20, v232
	v_fmac_f32_e32 v88, v21, v233
	v_fmac_f32_e32 v61, v22, v234
	v_fmac_f32_e32 v88, v23, v235
	ds_read_b128 v[228:231], v5 offset:34624
	s_waitcnt lgkmcnt(11)
	v_fmac_f32_e32 v61, v24, v146
	v_fmac_f32_e32 v88, v25, v147
	v_fmac_f32_e32 v61, v26, v148
	v_fmac_f32_e32 v88, v27, v149
	ds_read_b128 v[244:247], v5 offset:34672
	s_waitcnt lgkmcnt(11)
	v_fmac_f32_e32 v61, v28, v150
	v_fmac_f32_e32 v88, v29, v151
	v_fmac_f32_e32 v61, v30, v152
	v_fmac_f32_e32 v88, v31, v153
	ds_read_b128 v[232:235], v5 offset:34656
	v_add_f32_e32 v61, v61, v88
	v_sub_f32_e32 v61, v62, v61
	s_waitcnt lgkmcnt(10)
	v_fma_f32 v62, v16, v178, 0
	v_fma_f32 v76, v17, v179, 0
	v_fmac_f32_e32 v62, v18, v180
	v_fmac_f32_e32 v76, v19, v181
	ds_read_b128 v[146:149], v5 offset:27008
	v_fmac_f32_e32 v62, v20, v182
	v_fmac_f32_e32 v76, v21, v183
	v_fmac_f32_e32 v62, v22, v184
	v_fmac_f32_e32 v76, v23, v185
	ds_read_b128 v[150:153], v5 offset:27264
	s_waitcnt lgkmcnt(10)
	v_fmac_f32_e32 v62, v24, v190
	v_fmac_f32_e32 v76, v25, v191
	v_fmac_f32_e32 v62, v26, v192
	v_fmac_f32_e32 v76, v27, v193
	ds_read_b128 v[178:181], v5 offset:27520
	v_fmac_f32_e32 v62, v28, v186
	v_fmac_f32_e32 v76, v29, v187
	v_fmac_f32_e32 v62, v30, v188
	v_fmac_f32_e32 v76, v31, v189
	ds_read_b128 v[182:185], v5 offset:27776
	v_add_f32_e32 v62, v62, v76
	v_sub_f32_e32 v62, v63, v62
	s_mov_b64 exec, s[100:101]
	v_cvt_pk_bf16_f32 v238, -v31, s0
	global_store_short v[210:211], v238, off offset:3968
	s_not_b64 exec, s[100:101]
	global_store_dword v[154:155], v31, off offset:3840
	s_mov_b64 exec, -1
	s_waitcnt lgkmcnt(11)
	v_fma_f32 v63, v16, v198, 0
	v_fma_f32 v88, v17, v199, 0
	v_fmac_f32_e32 v63, v18, v200
	v_fmac_f32_e32 v88, v19, v201
	ds_read_b128 v[190:193], v5 offset:28032
	s_waitcnt lgkmcnt(11)
	v_fmac_f32_e32 v63, v20, v194
	v_fmac_f32_e32 v88, v21, v195
	v_fmac_f32_e32 v63, v22, v196
	v_fmac_f32_e32 v88, v23, v197
	ds_read_b128 v[186:189], v5 offset:28048
	s_waitcnt lgkmcnt(11)
	v_fmac_f32_e32 v63, v24, v206
	v_fmac_f32_e32 v88, v25, v207
	v_fmac_f32_e32 v63, v26, v208
	v_fmac_f32_e32 v88, v27, v209
	ds_read_b128 v[198:201], v5 offset:28288
	s_waitcnt lgkmcnt(11)
	v_fmac_f32_e32 v63, v28, v202
	v_fmac_f32_e32 v88, v29, v203
	v_fmac_f32_e32 v63, v30, v204
	v_fmac_f32_e32 v88, v31, v205
	ds_read_b128 v[194:197], v5 offset:28304
	v_add_f32_e32 v63, v63, v88
	v_sub_f32_e32 v63, v70, v63
	s_waitcnt lgkmcnt(10)
	v_fma_f32 v70, v16, v228, 0
	v_fma_f32 v76, v17, v229, 0
	v_fmac_f32_e32 v70, v18, v230
	v_fmac_f32_e32 v76, v19, v231
	ds_read_b128 v[206:209], v5 offset:28544
	v_fmac_f32_e32 v70, v20, v214
	v_fmac_f32_e32 v76, v21, v215
	v_fmac_f32_e32 v70, v22, v216
	v_fmac_f32_e32 v76, v23, v217
	ds_read_b128 v[202:205], v5 offset:28560
	s_waitcnt lgkmcnt(10)
	v_fmac_f32_e32 v70, v24, v232
	v_fmac_f32_e32 v76, v25, v233
	v_fmac_f32_e32 v70, v26, v234
	v_fmac_f32_e32 v76, v27, v235
	ds_read_b128 v[228:231], v5 offset:28800
	v_fmac_f32_e32 v70, v28, v244
	v_fmac_f32_e32 v76, v29, v245
	v_fmac_f32_e32 v70, v30, v246
	v_fmac_f32_e32 v76, v31, v247
	ds_read_b128 v[214:217], v5 offset:28816
	v_add_f32_e32 v70, v70, v76
	v_sub_f32_e32 v70, v71, v70
	s_waitcnt lgkmcnt(11)
	v_fma_f32 v71, -v32, v146, v33
	v_fma_f32 v33, -v33, v147, v71
	v_fma_f32 v33, -v34, v148, v33
	v_fma_f32 v33, -v35, v149, v33
	ds_read_b128 v[232:235], v5 offset:29056
	s_waitcnt lgkmcnt(11)
	v_fma_f32 v71, -v32, v150, v34
	v_fma_f32 v71, -v151, v33, v71
	v_fma_f32 v34, -v34, v152, v71
	v_fma_f32 v34, -v35, v153, v34
	ds_read_b128 v[244:247], v5 offset:29072
	s_waitcnt lgkmcnt(11)
	v_fma_f32 v71, -v32, v178, v35
	v_fma_f32 v71, -v179, v33, v71
	v_fma_f32 v71, -v180, v34, v71
	v_fma_f32 v35, -v35, v181, v71
	ds_read_b128 v[146:149], v5 offset:29088
	s_waitcnt lgkmcnt(11)
	v_fma_f32 v36, -v32, v182, v36
	v_fma_f32 v36, -v183, v33, v36
	v_fma_f32 v36, -v184, v34, v36
	v_fma_f32 v36, -v185, v35, v36
	ds_read_b128 v[150:153], v5 offset:29312
	s_waitcnt lgkmcnt(11)
	v_fma_f32 v71, -v32, v190, v37
	v_fma_f32 v71, -v191, v33, v71
	v_fma_f32 v71, -v192, v34, v71
	v_fma_f32 v71, -v193, v35, v71
	ds_read_b128 v[178:181], v5 offset:29328
	s_waitcnt lgkmcnt(11)
	v_fma_f32 v71, -v186, v36, v71
	v_fma_f32 v37, -v37, v187, v71
	v_fma_f32 v37, -v38, v188, v37
	v_fma_f32 v37, -v39, v189, v37
	ds_read_b128 v[182:185], v5 offset:29344
	s_waitcnt lgkmcnt(11)
	v_fma_f32 v71, -v32, v198, v38
	v_fma_f32 v71, -v33, v199, v71
	v_fma_f32 v71, -v200, v34, v71
	v_fma_f32 v71, -v201, v35, v71
	ds_read_b128 v[190:193], v5 offset:29568
	s_waitcnt lgkmcnt(11)
	v_fma_f32 v71, -v194, v36, v71
	v_fma_f32 v71, -v195, v37, v71
	v_fma_f32 v38, -v38, v196, v71
	v_fma_f32 v38, -v39, v197, v38
	ds_read_b128 v[186:189], v5 offset:29584
	s_waitcnt lgkmcnt(11)
	v_fma_f32 v71, -v32, v206, v39
	v_fma_f32 v71, -v33, v207, v71
	v_fma_f32 v71, -v208, v34, v71
	v_fma_f32 v71, -v209, v35, v71
	ds_read_b128 v[198:201], v5 offset:29600
	s_waitcnt lgkmcnt(11)
	v_fma_f32 v71, -v202, v36, v71
	v_fma_f32 v71, -v203, v37, v71
	v_fma_f32 v71, -v204, v38, v71
	v_fma_f32 v39, -v39, v205, v71
	ds_read_b128 v[194:197], v5 offset:29824
	s_waitcnt lgkmcnt(11)
	v_fma_f32 v40, -v32, v228, v40
	v_fma_f32 v40, -v33, v229, v40
	v_fma_f32 v40, -v34, v230, v40
	v_fma_f32 v40, -v231, v35, v40
	ds_read_b128 v[206:209], v5 offset:29840
	s_waitcnt lgkmcnt(11)
	v_fma_f32 v40, -v214, v36, v40
	v_fma_f32 v40, -v215, v37, v40
	v_fma_f32 v40, -v216, v38, v40
	v_fma_f32 v40, -v217, v39, v40
	ds_read_b128 v[202:205], v5 offset:29856
	s_waitcnt lgkmcnt(11)
	v_fma_f32 v71, -v32, v232, v41
	v_fma_f32 v71, -v33, v233, v71
	v_fma_f32 v71, -v34, v234, v71
	v_fma_f32 v71, -v235, v35, v71
	ds_read_b128 v[228:231], v5 offset:30080
	s_waitcnt lgkmcnt(11)
	v_fma_f32 v71, -v244, v36, v71
	v_fma_f32 v71, -v245, v37, v71
	v_fma_f32 v71, -v246, v38, v71
	v_fma_f32 v71, -v247, v39, v71
	ds_read_b128 v[214:217], v5 offset:30096
	s_waitcnt lgkmcnt(11)
	v_fma_f32 v71, -v146, v40, v71
	v_fma_f32 v41, -v41, v147, v71
	v_fma_f32 v41, -v42, v148, v41
	v_fma_f32 v41, -v43, v149, v41
	ds_read_b128 v[232:235], v5 offset:30112
	s_waitcnt lgkmcnt(11)
	v_fma_f32 v71, -v32, v150, v42
	v_fma_f32 v71, -v33, v151, v71
	v_fma_f32 v71, -v34, v152, v71
	v_fma_f32 v71, -v35, v153, v71
	ds_read_b128 v[244:247], v5 offset:30128
	s_waitcnt lgkmcnt(11)
	v_fma_f32 v71, -v36, v178, v71
	v_fma_f32 v71, -v179, v37, v71
	v_fma_f32 v71, -v180, v38, v71
	v_fma_f32 v71, -v181, v39, v71
	ds_read_b128 v[146:149], v5 offset:30336
	s_waitcnt lgkmcnt(11)
	v_fma_f32 v71, -v182, v40, v71
	v_fma_f32 v71, -v183, v41, v71
	v_fma_f32 v42, -v42, v184, v71
	v_fma_f32 v42, -v43, v185, v42
	ds_read_b128 v[150:153], v5 offset:30352
	s_waitcnt lgkmcnt(11)
	v_fma_f32 v71, -v32, v190, v43
	v_fma_f32 v71, -v33, v191, v71
	v_fma_f32 v71, -v34, v192, v71
	v_fma_f32 v71, -v35, v193, v71
	ds_read_b128 v[178:181], v5 offset:30368
	s_waitcnt lgkmcnt(11)
	v_fma_f32 v71, -v36, v186, v71
	v_fma_f32 v71, -v187, v37, v71
	v_fma_f32 v71, -v188, v38, v71
	v_fma_f32 v71, -v189, v39, v71
	ds_read_b128 v[182:185], v5 offset:30384
	s_waitcnt lgkmcnt(11)
	v_fma_f32 v71, -v198, v40, v71
	v_fma_f32 v71, -v199, v41, v71
	v_fma_f32 v71, -v200, v42, v71
	v_fma_f32 v43, -v43, v201, v71
	ds_read_b128 v[190:193], v5 offset:30592
	s_waitcnt lgkmcnt(11)
	v_fma_f32 v44, -v32, v194, v44
	v_fma_f32 v44, -v33, v195, v44
	v_fma_f32 v44, -v34, v196, v44
	v_fma_f32 v44, -v35, v197, v44
	ds_read_b128 v[186:189], v5 offset:30608
	s_waitcnt lgkmcnt(11)
	v_fma_f32 v44, -v36, v206, v44
	v_fma_f32 v44, -v37, v207, v44
	v_fma_f32 v44, -v208, v38, v44
	v_fma_f32 v44, -v209, v39, v44
	ds_read_b128 v[198:201], v5 offset:30624
	s_waitcnt lgkmcnt(11)
	v_fma_f32 v44, -v202, v40, v44
	v_fma_f32 v44, -v203, v41, v44
	v_fma_f32 v44, -v204, v42, v44
	v_fma_f32 v44, -v205, v43, v44
	ds_read_b128 v[194:197], v5 offset:30640
	s_waitcnt lgkmcnt(11)
	v_fma_f32 v71, -v32, v228, v45
	v_fma_f32 v71, -v33, v229, v71
	v_fma_f32 v71, -v34, v230, v71
	v_fma_f32 v71, -v35, v231, v71
	ds_read_b128 v[206:209], v5 offset:30848
	s_waitcnt lgkmcnt(11)
	v_fma_f32 v71, -v36, v214, v71
	v_fma_f32 v71, -v37, v215, v71
	v_fma_f32 v71, -v38, v216, v71
	v_fma_f32 v71, -v217, v39, v71
	ds_read_b128 v[202:205], v5 offset:30864
	s_waitcnt lgkmcnt(11)
	v_fma_f32 v71, -v232, v40, v71
	v_fma_f32 v71, -v233, v41, v71
	v_fma_f32 v71, -v234, v42, v71
	v_fma_f32 v71, -v235, v43, v71
	ds_read_b128 v[228:231], v5 offset:30880
	s_waitcnt lgkmcnt(11)
	v_fma_f32 v71, -v244, v44, v71
	v_fma_f32 v45, -v45, v245, v71
	v_fma_f32 v45, -v46, v246, v45
	v_fma_f32 v45, -v47, v247, v45
	ds_read_b128 v[214:217], v5 offset:30896
	s_waitcnt lgkmcnt(11)
	v_fma_f32 v71, -v32, v146, v46
	v_fma_f32 v71, -v33, v147, v71
	v_fma_f32 v71, -v34, v148, v71
	v_fma_f32 v71, -v35, v149, v71
	ds_read_b128 v[232:235], v5 offset:31120
	s_waitcnt lgkmcnt(11)
	v_fma_f32 v71, -v36, v150, v71
	v_fma_f32 v71, -v37, v151, v71
	v_fma_f32 v71, -v38, v152, v71
	v_fma_f32 v71, -v39, v153, v71
	ds_read_b128 v[244:247], v5 offset:31104
	s_waitcnt lgkmcnt(11)
	v_fma_f32 v71, -v40, v178, v71
	v_fma_f32 v71, -v179, v41, v71
	v_fma_f32 v71, -v180, v42, v71
	v_fma_f32 v71, -v181, v43, v71
	ds_read_b128 v[146:149], v5 offset:31152
	s_waitcnt lgkmcnt(11)
	v_fma_f32 v71, -v182, v44, v71
	v_fma_f32 v71, -v183, v45, v71
	v_fma_f32 v46, -v46, v184, v71
	v_fma_f32 v46, -v47, v185, v46
	ds_read_b128 v[150:153], v5 offset:31136
	s_waitcnt lgkmcnt(11)
	v_fma_f32 v71, -v32, v190, v47
	v_fma_f32 v71, -v33, v191, v71
	v_fma_f32 v71, -v34, v192, v71
	v_fma_f32 v71, -v35, v193, v71
	ds_read_b128 v[178:181], v5 offset:31360
	s_waitcnt lgkmcnt(11)
	v_fma_f32 v71, -v36, v186, v71
	v_fma_f32 v71, -v37, v187, v71
	v_fma_f32 v71, -v38, v188, v71
	v_fma_f32 v71, -v39, v189, v71
	ds_read_b128 v[182:185], v5 offset:31376
	s_waitcnt lgkmcnt(11)
	v_fma_f32 v71, -v40, v198, v71
	v_fma_f32 v71, -v41, v199, v71
	v_fma_f32 v71, -v200, v42, v71
	v_fma_f32 v71, -v201, v43, v71
	ds_read_b128 v[190:193], v5 offset:31392
	s_waitcnt lgkmcnt(11)
	v_fma_f32 v71, -v194, v44, v71
	v_fma_f32 v71, -v195, v45, v71
	v_fma_f32 v71, -v196, v46, v71
	v_fma_f32 v47, -v47, v197, v71
	ds_read_b128 v[186:189], v5 offset:31408
	s_mov_b64 s[100:101], 0x1000
	v_lshl_add_u64 v[154:155], v[154:155], 0, s[100:101]
	v_lshl_add_u64 v[210:211], v[210:211], 0, s[100:101]
	v_readlane_b32 s100, v253, 32
	v_readlane_b32 s101, v253, 33
	s_nop 3
	s_mov_b64 exec, s[100:101]
	v_cvt_pk_bf16_f32 v238, -v32, s0
	global_store_short v[210:211], v238, off
	s_not_b64 exec, s[100:101]
	global_store_dword v[154:155], v32, off
	s_mov_b64 exec, -1
	s_mov_b64 exec, s[100:101]
	v_cvt_pk_bf16_f32 v238, -v33, s0
	global_store_short v[210:211], v238, off offset:128
	s_not_b64 exec, s[100:101]
	global_store_dword v[154:155], v33, off offset:256
	s_mov_b64 exec, -1
	s_waitcnt lgkmcnt(11)
	v_fma_f32 v71, v32, v206, 0
	v_fma_f32 v88, v33, v207, 0
	v_fmac_f32_e32 v71, v34, v208
	v_fmac_f32_e32 v88, v35, v209
	ds_read_b128 v[198:201], v5 offset:31632
	s_waitcnt lgkmcnt(11)
	v_fmac_f32_e32 v71, v36, v202
	v_fmac_f32_e32 v88, v37, v203
	v_fmac_f32_e32 v71, v38, v204
	v_fmac_f32_e32 v88, v39, v205
	ds_read_b128 v[194:197], v5 offset:31616
	s_waitcnt lgkmcnt(11)
	v_fmac_f32_e32 v71, v40, v228
	v_fmac_f32_e32 v88, v41, v229
	v_fmac_f32_e32 v71, v42, v230
	v_fmac_f32_e32 v88, v231, v43
	ds_read_b128 v[206:209], v5 offset:31664
	s_waitcnt lgkmcnt(11)
	v_fmac_f32_e32 v71, v214, v44
	v_fmac_f32_e32 v88, v215, v45
	v_fmac_f32_e32 v71, v216, v46
	v_fmac_f32_e32 v88, v217, v47
	ds_read_b128 v[202:205], v5 offset:31648
	v_add_f32_e32 v71, v71, v88
	v_sub_f32_e32 v48, v48, v71
	s_waitcnt lgkmcnt(10)
	v_fma_f32 v71, v32, v244, 0
	v_fma_f32 v76, v33, v245, 0
	v_fmac_f32_e32 v71, v34, v246
	v_fmac_f32_e32 v76, v35, v247
	ds_read_b128 v[228:231], v5 offset:31872
	v_fmac_f32_e32 v71, v36, v232
	v_fmac_f32_e32 v76, v37, v233
	v_fmac_f32_e32 v71, v38, v234
	v_fmac_f32_e32 v76, v39, v235
	ds_read_b128 v[214:217], v5 offset:31888
	s_waitcnt lgkmcnt(10)
	v_fmac_f32_e32 v71, v40, v150
	v_fmac_f32_e32 v76, v41, v151
	v_fmac_f32_e32 v71, v42, v152
	v_fmac_f32_e32 v76, v43, v153
	ds_read_b128 v[244:247], v5 offset:31904
	v_fmac_f32_e32 v71, v146, v44
	v_fmac_f32_e32 v76, v147, v45
	v_fmac_f32_e32 v71, v148, v46
	v_fmac_f32_e32 v76, v149, v47
	ds_read_b128 v[232:235], v5 offset:31920
	v_add_f32_e32 v71, v71, v76
	v_sub_f32_e32 v49, v49, v71
	s_mov_b64 exec, s[100:101]
	v_cvt_pk_bf16_f32 v238, -v34, s0
	global_store_short v[210:211], v238, off offset:256
	s_not_b64 exec, s[100:101]
	global_store_dword v[154:155], v34, off offset:512
	s_mov_b64 exec, -1
	s_mov_b64 exec, s[100:101]
	v_cvt_pk_bf16_f32 v238, -v35, s0
	global_store_short v[210:211], v238, off offset:384
	s_not_b64 exec, s[100:101]
	global_store_dword v[154:155], v35, off offset:768
	s_mov_b64 exec, -1
	s_waitcnt lgkmcnt(11)
	v_fma_f32 v71, v32, v178, 0
	v_fma_f32 v88, v33, v179, 0
	v_fmac_f32_e32 v71, v34, v180
	v_fmac_f32_e32 v88, v35, v181
	ds_read_b128 v[150:153], v5 offset:32144
	s_waitcnt lgkmcnt(11)
	v_fmac_f32_e32 v71, v36, v182
	v_fmac_f32_e32 v88, v37, v183
	v_fmac_f32_e32 v71, v38, v184
	v_fmac_f32_e32 v88, v39, v185
	ds_read_b128 v[146:149], v5 offset:32128
	s_waitcnt lgkmcnt(11)
	v_fmac_f32_e32 v71, v40, v190
	v_fmac_f32_e32 v88, v41, v191
	v_fmac_f32_e32 v71, v42, v192
	v_fmac_f32_e32 v88, v43, v193
	ds_read_b128 v[178:181], v5 offset:32176
	s_waitcnt lgkmcnt(11)
	v_fmac_f32_e32 v71, v44, v186
	v_fmac_f32_e32 v88, v45, v187
	v_fmac_f32_e32 v71, v188, v46
	v_fmac_f32_e32 v88, v189, v47
	ds_read_b128 v[182:185], v5 offset:32160
	v_add_f32_e32 v71, v71, v88
	v_sub_f32_e32 v50, v50, v71
	s_waitcnt lgkmcnt(10)
	v_fma_f32 v71, v32, v194, 0
	v_fma_f32 v76, v33, v195, 0
	v_fmac_f32_e32 v71, v34, v196
	v_fmac_f32_e32 v76, v35, v197
	ds_read_b128 v[190:193], v5 offset:32384
	v_fmac_f32_e32 v71, v36, v198
	v_fmac_f32_e32 v76, v37, v199
	v_fmac_f32_e32 v71, v38, v200
	v_fmac_f32_e32 v76, v39, v201
	ds_read_b128 v[186:189], v5 offset:32400
	s_waitcnt lgkmcnt(10)
	v_fmac_f32_e32 v71, v40, v202
	v_fmac_f32_e32 v76, v41, v203
	v_fmac_f32_e32 v71, v42, v204
	v_fmac_f32_e32 v76, v43, v205
	ds_read_b128 v[194:197], v5 offset:32416
	v_fmac_f32_e32 v71, v44, v206
	v_fmac_f32_e32 v76, v45, v207
	v_fmac_f32_e32 v71, v208, v46
	v_fmac_f32_e32 v76, v209, v47
	ds_read_b128 v[198:201], v5 offset:32432
	v_add_f32_e32 v71, v71, v76
	v_sub_f32_e32 v51, v51, v71
	s_mov_b64 exec, s[100:101]
	v_cvt_pk_bf16_f32 v238, -v36, s0
	global_store_short v[210:211], v238, off offset:512
	s_not_b64 exec, s[100:101]
	global_store_dword v[154:155], v36, off offset:1024
	s_mov_b64 exec, -1
	s_mov_b64 exec, s[100:101]
	v_cvt_pk_bf16_f32 v238, -v37, s0
	global_store_short v[210:211], v238, off offset:640
	s_not_b64 exec, s[100:101]
	global_store_dword v[154:155], v37, off offset:1280
	s_mov_b64 exec, -1
	s_waitcnt lgkmcnt(11)
	v_fma_f32 v71, v32, v228, 0
	v_fma_f32 v88, v33, v229, 0
	v_fmac_f32_e32 v71, v34, v230
	v_fmac_f32_e32 v88, v35, v231
	ds_read_b128 v[202:205], v5 offset:32656
	s_waitcnt lgkmcnt(11)
	v_fmac_f32_e32 v71, v36, v214
	v_fmac_f32_e32 v88, v37, v215
	v_fmac_f32_e32 v71, v38, v216
	v_fmac_f32_e32 v88, v39, v217
	ds_read_b128 v[206:209], v5 offset:32640
	s_waitcnt lgkmcnt(11)
	v_fmac_f32_e32 v71, v40, v244
	v_fmac_f32_e32 v88, v41, v245
	v_fmac_f32_e32 v71, v42, v246
	v_fmac_f32_e32 v88, v43, v247
	ds_read_b128 v[228:231], v5 offset:32688
	s_waitcnt lgkmcnt(11)
	v_fmac_f32_e32 v71, v44, v232
	v_fmac_f32_e32 v88, v45, v233
	v_fmac_f32_e32 v71, v46, v234
	v_fmac_f32_e32 v88, v47, v235
	ds_read_b128 v[214:217], v5 offset:32672
	v_add_f32_e32 v71, v71, v88
	v_sub_f32_e32 v52, v52, v71
	s_waitcnt lgkmcnt(10)
	v_fma_f32 v71, v32, v146, 0
	v_fma_f32 v76, v33, v147, 0
	v_fmac_f32_e32 v71, v34, v148
	v_fmac_f32_e32 v76, v35, v149
	ds_read_b128 v[244:247], v5 offset:32896
	v_fmac_f32_e32 v71, v36, v150
	v_fmac_f32_e32 v76, v37, v151
	v_fmac_f32_e32 v71, v38, v152
	v_fmac_f32_e32 v76, v39, v153
	ds_read_b128 v[232:235], v5 offset:32912
	s_waitcnt lgkmcnt(10)
	v_fmac_f32_e32 v71, v40, v182
	v_fmac_f32_e32 v76, v41, v183
	v_fmac_f32_e32 v71, v42, v184
	v_fmac_f32_e32 v76, v43, v185
	ds_read_b128 v[146:149], v5 offset:32928
	v_fmac_f32_e32 v71, v44, v178
	v_fmac_f32_e32 v76, v45, v179
	v_fmac_f32_e32 v71, v46, v180
	v_fmac_f32_e32 v76, v47, v181
	ds_read_b128 v[150:153], v5 offset:32944
	v_add_f32_e32 v71, v71, v76
	v_sub_f32_e32 v53, v53, v71
	s_mov_b64 exec, s[100:101]
	v_cvt_pk_bf16_f32 v238, -v38, s0
	global_store_short v[210:211], v238, off offset:768
	s_not_b64 exec, s[100:101]
	global_store_dword v[154:155], v38, off offset:1536
	s_mov_b64 exec, -1
	s_mov_b64 exec, s[100:101]
	v_cvt_pk_bf16_f32 v238, -v39, s0
	global_store_short v[210:211], v238, off offset:896
	s_not_b64 exec, s[100:101]
	global_store_dword v[154:155], v39, off offset:1792
	s_mov_b64 exec, -1
	s_waitcnt lgkmcnt(11)
	v_fma_f32 v71, v32, v190, 0
	v_fma_f32 v88, v33, v191, 0
	v_fmac_f32_e32 v71, v34, v192
	v_fmac_f32_e32 v88, v35, v193
	ds_read_b128 v[182:185], v5 offset:33168
	s_waitcnt lgkmcnt(11)
	v_fmac_f32_e32 v71, v36, v186
	v_fmac_f32_e32 v88, v37, v187
	v_fmac_f32_e32 v71, v38, v188
	v_fmac_f32_e32 v88, v39, v189
	ds_read_b128 v[178:181], v5 offset:33152
	s_waitcnt lgkmcnt(11)
	v_fmac_f32_e32 v71, v40, v194
	v_fmac_f32_e32 v88, v41, v195
	v_fmac_f32_e32 v71, v42, v196
	v_fmac_f32_e32 v88, v43, v197
	ds_read_b128 v[190:193], v5 offset:33200
	s_waitcnt lgkmcnt(11)
	v_fmac_f32_e32 v71, v44, v198
	v_fmac_f32_e32 v88, v45, v199
	v_fmac_f32_e32 v71, v46, v200
	v_fmac_f32_e32 v88, v47, v201
	ds_read_b128 v[186:189], v5 offset:33184
	v_add_f32_e32 v71, v71, v88
	v_sub_f32_e32 v77, v54, v71
	s_waitcnt lgkmcnt(10)
	v_fma_f32 v54, v32, v206, 0
	v_fma_f32 v71, v33, v207, 0
	v_fmac_f32_e32 v54, v34, v208
	v_fmac_f32_e32 v71, v35, v209
	ds_read_b128 v[194:197], v5 offset:33408
	v_fmac_f32_e32 v54, v36, v202
	v_fmac_f32_e32 v71, v37, v203
	v_fmac_f32_e32 v54, v38, v204
	v_fmac_f32_e32 v71, v39, v205
	ds_read_b128 v[198:201], v5 offset:33424
	s_waitcnt lgkmcnt(10)
	v_fmac_f32_e32 v54, v40, v214
	v_fmac_f32_e32 v71, v41, v215
	v_fmac_f32_e32 v54, v42, v216
	v_fmac_f32_e32 v71, v43, v217
	ds_read_b128 v[206:209], v5 offset:33440
	v_fmac_f32_e32 v54, v44, v228
	v_fmac_f32_e32 v71, v45, v229
	v_fmac_f32_e32 v54, v46, v230
	v_fmac_f32_e32 v71, v47, v231
	ds_read_b128 v[202:205], v5 offset:33456
	v_add_f32_e32 v54, v54, v71
	v_sub_f32_e32 v75, v55, v54
	s_mov_b64 exec, s[100:101]
	v_cvt_pk_bf16_f32 v238, -v40, s0
	global_store_short v[210:211], v238, off offset:1024
	s_not_b64 exec, s[100:101]
	global_store_dword v[154:155], v40, off offset:2048
	s_mov_b64 exec, -1
	s_mov_b64 exec, s[100:101]
	v_cvt_pk_bf16_f32 v238, -v41, s0
	global_store_short v[210:211], v238, off offset:1152
	s_not_b64 exec, s[100:101]
	global_store_dword v[154:155], v41, off offset:2304
	s_mov_b64 exec, -1
	s_waitcnt lgkmcnt(11)
	v_fma_f32 v54, v32, v244, 0
	v_fma_f32 v55, v33, v245, 0
	v_fmac_f32_e32 v54, v34, v246
	v_fmac_f32_e32 v55, v35, v247
	ds_read_b128 v[214:217], v5 offset:33680
	s_waitcnt lgkmcnt(11)
	v_fmac_f32_e32 v54, v36, v232
	v_fmac_f32_e32 v55, v37, v233
	v_fmac_f32_e32 v54, v38, v234
	v_fmac_f32_e32 v55, v39, v235
	ds_read_b128 v[228:231], v5 offset:33664
	s_waitcnt lgkmcnt(11)
	v_fmac_f32_e32 v54, v40, v146
	v_fmac_f32_e32 v55, v41, v147
	v_fmac_f32_e32 v54, v42, v148
	v_fmac_f32_e32 v55, v43, v149
	ds_read_b128 v[244:247], v5 offset:33712
	s_waitcnt lgkmcnt(11)
	v_fmac_f32_e32 v54, v44, v150
	v_fmac_f32_e32 v55, v45, v151
	v_fmac_f32_e32 v54, v46, v152
	v_fmac_f32_e32 v55, v47, v153
	ds_read_b128 v[232:235], v5 offset:33696
	v_add_f32_e32 v54, v54, v55
	v_sub_f32_e32 v76, v56, v54
	s_waitcnt lgkmcnt(10)
	v_fma_f32 v54, v32, v178, 0
	v_fma_f32 v55, v33, v179, 0
	v_fmac_f32_e32 v54, v34, v180
	v_fmac_f32_e32 v55, v35, v181
	ds_read_b128 v[146:149], v5 offset:33920
	v_fmac_f32_e32 v54, v36, v182
	v_fmac_f32_e32 v55, v37, v183
	v_fmac_f32_e32 v54, v38, v184
	v_fmac_f32_e32 v55, v39, v185
	ds_read_b128 v[150:153], v5 offset:33936
	s_waitcnt lgkmcnt(10)
	v_fmac_f32_e32 v54, v40, v186
	v_fmac_f32_e32 v55, v41, v187
	v_fmac_f32_e32 v54, v42, v188
	v_fmac_f32_e32 v55, v43, v189
	ds_read_b128 v[178:181], v5 offset:33952
	v_fmac_f32_e32 v54, v44, v190
	v_fmac_f32_e32 v55, v45, v191
	v_fmac_f32_e32 v54, v46, v192
	v_fmac_f32_e32 v55, v47, v193
	ds_read_b128 v[182:185], v5 offset:33968
	v_add_f32_e32 v54, v54, v55
	v_sub_f32_e32 v74, v57, v54
	s_mov_b64 exec, s[100:101]
	v_cvt_pk_bf16_f32 v238, -v42, s0
	global_store_short v[210:211], v238, off offset:1280
	s_not_b64 exec, s[100:101]
	global_store_dword v[154:155], v42, off offset:2560
	s_mov_b64 exec, -1
	s_mov_b64 exec, s[100:101]
	v_cvt_pk_bf16_f32 v238, -v43, s0
	global_store_short v[210:211], v238, off offset:1408
	s_not_b64 exec, s[100:101]
	global_store_dword v[154:155], v43, off offset:2816
	s_mov_b64 exec, -1
	s_waitcnt lgkmcnt(11)
	v_fma_f32 v71, v32, v194, 0
	v_fma_f32 v72, v33, v195, 0
	v_fmac_f32_e32 v71, v34, v196
	v_fmac_f32_e32 v72, v35, v197
	ds_read_b128 v[186:189], v5 offset:34192
	s_waitcnt lgkmcnt(11)
	v_fmac_f32_e32 v71, v36, v198
	v_fmac_f32_e32 v72, v37, v199
	v_fmac_f32_e32 v71, v38, v200
	v_fmac_f32_e32 v72, v39, v201
	ds_read_b128 v[190:193], v5 offset:34176
	s_waitcnt lgkmcnt(11)
	v_fmac_f32_e32 v71, v40, v206
	v_fmac_f32_e32 v72, v41, v207
	v_fmac_f32_e32 v71, v42, v208
	v_fmac_f32_e32 v72, v43, v209
	ds_read_b128 v[194:197], v5 offset:34224
	s_waitcnt lgkmcnt(11)
	v_fmac_f32_e32 v71, v44, v202
	v_fmac_f32_e32 v72, v45, v203
	v_fmac_f32_e32 v71, v46, v204
	v_fmac_f32_e32 v72, v47, v205
	ds_read_b128 v[198:201], v5 offset:34208
	v_add_f32_e32 v71, v71, v72
	v_sub_f32_e32 v73, v58, v71
	s_waitcnt lgkmcnt(10)
	v_fma_f32 v58, v32, v228, 0
	v_fma_f32 v71, v33, v229, 0
	v_fmac_f32_e32 v58, v34, v230
	v_fmac_f32_e32 v71, v35, v231
	ds_read_b128 v[206:209], v5 offset:34432
	v_fmac_f32_e32 v58, v36, v214
	v_fmac_f32_e32 v71, v37, v215
	v_fmac_f32_e32 v58, v38, v216
	v_fmac_f32_e32 v71, v39, v217
	ds_read_b128 v[202:205], v5 offset:34448
	s_waitcnt lgkmcnt(10)
	v_fmac_f32_e32 v58, v40, v232
	v_fmac_f32_e32 v71, v41, v233
	v_fmac_f32_e32 v58, v42, v234
	v_fmac_f32_e32 v71, v43, v235
	ds_read_b128 v[228:231], v5 offset:34464
	v_fmac_f32_e32 v58, v44, v244
	v_fmac_f32_e32 v71, v45, v245
	v_fmac_f32_e32 v58, v46, v246
	v_fmac_f32_e32 v71, v47, v247
	ds_read_b128 v[214:217], v5 offset:34480
	v_add_f32_e32 v54, v58, v71
	v_sub_f32_e32 v72, v59, v54
	s_mov_b64 exec, s[100:101]
	v_cvt_pk_bf16_f32 v238, -v44, s0
	global_store_short v[210:211], v238, off offset:1536
	s_not_b64 exec, s[100:101]
	global_store_dword v[154:155], v44, off offset:3072
	s_mov_b64 exec, -1
	s_mov_b64 exec, s[100:101]
	v_cvt_pk_bf16_f32 v238, -v45, s0
	global_store_short v[210:211], v238, off offset:1664
	s_not_b64 exec, s[100:101]
	global_store_dword v[154:155], v45, off offset:3328
	s_mov_b64 exec, -1
	s_waitcnt lgkmcnt(11)
	v_fma_f32 v58, v32, v146, 0
	v_fma_f32 v59, v33, v147, 0
	v_fmac_f32_e32 v58, v34, v148
	v_fmac_f32_e32 v59, v35, v149
	ds_read_b128 v[232:235], v5 offset:34704
	s_waitcnt lgkmcnt(11)
	v_fmac_f32_e32 v58, v36, v150
	v_fmac_f32_e32 v59, v37, v151
	v_fmac_f32_e32 v58, v38, v152
	v_fmac_f32_e32 v59, v39, v153
	ds_read_b128 v[244:247], v5 offset:34688
	ds_read_b128 v[146:149], v5 offset:34736
	ds_read_b128 v[150:153], v5 offset:34720
	s_waitcnt lgkmcnt(13)
	v_fmac_f32_e32 v58, v40, v178
	v_fmac_f32_e32 v59, v41, v179
	v_fmac_f32_e32 v58, v42, v180
	v_fmac_f32_e32 v59, v43, v181
	ds_read_b128 v[178:181], v5 offset:31168
	s_waitcnt lgkmcnt(13)
	v_fmac_f32_e32 v58, v44, v182
	v_fmac_f32_e32 v59, v45, v183
	v_fmac_f32_e32 v58, v46, v184
	v_fmac_f32_e32 v59, v47, v185
	ds_read_b128 v[182:185], v5 offset:31424
	v_add_f32_e32 v58, v58, v59
	v_sub_f32_e32 v71, v61, v58
	s_waitcnt lgkmcnt(12)
	v_fma_f32 v58, v32, v190, 0
	v_fma_f32 v59, v33, v191, 0
	v_fmac_f32_e32 v58, v34, v192
	v_fmac_f32_e32 v59, v35, v193
	ds_read_b128 v[190:193], v5 offset:31680
	v_fmac_f32_e32 v58, v36, v186
	v_fmac_f32_e32 v59, v37, v187
	v_fmac_f32_e32 v58, v38, v188
	v_fmac_f32_e32 v59, v39, v189
	ds_read_b128 v[186:189], v5 offset:31936
	s_waitcnt lgkmcnt(12)
	v_fmac_f32_e32 v58, v40, v198
	v_fmac_f32_e32 v59, v41, v199
	v_fmac_f32_e32 v58, v42, v200
	v_fmac_f32_e32 v59, v43, v201
	ds_read_b128 v[198:201], v5 offset:32192
	v_fmac_f32_e32 v58, v44, v194
	v_fmac_f32_e32 v59, v45, v195
	v_fmac_f32_e32 v58, v46, v196
	v_fmac_f32_e32 v59, v47, v197
	ds_read_b128 v[194:197], v5 offset:32208
	v_add_f32_e32 v54, v58, v59
	v_sub_f32_e32 v59, v62, v54
	s_mov_b64 exec, s[100:101]
	v_cvt_pk_bf16_f32 v238, -v46, s0
	global_store_short v[210:211], v238, off offset:1792
	s_not_b64 exec, s[100:101]
	global_store_dword v[154:155], v46, off offset:3584
	s_mov_b64 exec, -1
	s_mov_b64 exec, s[100:101]
	v_cvt_pk_bf16_f32 v238, -v47, s0
	global_store_short v[210:211], v238, off offset:1920
	s_not_b64 exec, s[100:101]
	global_store_dword v[154:155], v47, off offset:3840
	s_mov_b64 exec, -1
	s_waitcnt lgkmcnt(13)
	v_fma_f32 v54, v32, v206, 0
	v_fma_f32 v55, v33, v207, 0
	v_fmac_f32_e32 v54, v34, v208
	v_fmac_f32_e32 v55, v35, v209
	ds_read_b128 v[206:209], v5 offset:32448
	s_waitcnt lgkmcnt(13)
	v_fmac_f32_e32 v54, v36, v202
	v_fmac_f32_e32 v55, v37, v203
	v_fmac_f32_e32 v54, v38, v204
	v_fmac_f32_e32 v55, v39, v205
	ds_read_b128 v[202:205], v5 offset:32464
	s_waitcnt lgkmcnt(13)
	v_fmac_f32_e32 v54, v40, v228
	v_fmac_f32_e32 v55, v41, v229
	v_fmac_f32_e32 v54, v42, v230
	v_fmac_f32_e32 v55, v43, v231
	ds_read_b128 v[228:231], v5 offset:32704
	s_waitcnt lgkmcnt(13)
	v_fmac_f32_e32 v54, v44, v214
	v_fmac_f32_e32 v55, v45, v215
	v_fmac_f32_e32 v54, v46, v216
	v_fmac_f32_e32 v55, v47, v217
	ds_read_b128 v[214:217], v5 offset:32720
	v_add_f32_e32 v54, v54, v55
	v_sub_f32_e32 v57, v63, v54
	s_waitcnt lgkmcnt(12)
	v_fma_f32 v54, v32, v244, 0
	v_fma_f32 v55, v33, v245, 0
	v_fmac_f32_e32 v54, v34, v246
	v_fmac_f32_e32 v55, v35, v247
	v_fmac_f32_e32 v54, v36, v232
	v_fmac_f32_e32 v55, v37, v233
	v_fmac_f32_e32 v54, v38, v234
	v_fmac_f32_e32 v55, v39, v235
	ds_read_b128 v[232:235], v5 offset:32960
	s_waitcnt lgkmcnt(11)
	v_fmac_f32_e32 v54, v40, v150
	v_fmac_f32_e32 v55, v41, v151
	v_fmac_f32_e32 v54, v42, v152
	v_fmac_f32_e32 v55, v43, v153
	v_fmac_f32_e32 v54, v44, v146
	v_fmac_f32_e32 v55, v45, v147
	v_fmac_f32_e32 v54, v46, v148
	v_fmac_f32_e32 v55, v47, v149
	v_add_f32_e32 v54, v54, v55
	v_sub_f32_e32 v54, v70, v54
	s_waitcnt lgkmcnt(10)
	v_fma_f32 v55, -v48, v178, v49
	v_fma_f32 v49, -v49, v179, v55
	v_fma_f32 v49, -v50, v180, v49
	v_fma_f32 v49, -v51, v181, v49
	ds_read_b128 v[178:181], v5 offset:32976
	s_waitcnt lgkmcnt(10)
	v_fma_f32 v55, -v48, v182, v50
	v_fma_f32 v55, -v183, v49, v55
	v_fma_f32 v50, -v50, v184, v55
	v_fma_f32 v50, -v51, v185, v50
	ds_read_b128 v[182:185], v5 offset:33216
	s_waitcnt lgkmcnt(10)
	v_fma_f32 v55, -v48, v190, v51
	v_fma_f32 v55, -v191, v49, v55
	v_fma_f32 v55, -v192, v50, v55
	v_fma_f32 v51, -v51, v193, v55
	ds_read_b128 v[190:193], v5 offset:33232
	s_waitcnt lgkmcnt(10)
	v_fma_f32 v52, -v48, v186, v52
	v_fma_f32 v52, -v187, v49, v52
	v_fma_f32 v52, -v188, v50, v52
	v_fma_f32 v52, -v189, v51, v52
	ds_read_b128 v[186:189], v5 offset:33248
	s_waitcnt lgkmcnt(10)
	v_fma_f32 v55, -v48, v198, v53
	v_fma_f32 v55, -v199, v49, v55
	v_fma_f32 v55, -v200, v50, v55
	v_fma_f32 v55, -v201, v51, v55
	ds_read_b128 v[198:201], v5 offset:33472
	s_waitcnt lgkmcnt(10)
	v_fma_f32 v55, -v194, v52, v55
	v_fma_f32 v53, -v53, v195, v55
	v_fma_f32 v53, -v77, v196, v53
	v_fma_f32 v53, -v75, v197, v53
	ds_read_b128 v[194:197], v5 offset:33488
	s_waitcnt lgkmcnt(10)
	v_fma_f32 v55, -v48, v206, v77
	v_fma_f32 v55, -v49, v207, v55
	v_fma_f32 v55, -v208, v50, v55
	v_fma_f32 v55, -v209, v51, v55
	ds_read_b128 v[206:209], v5 offset:33504
	s_waitcnt lgkmcnt(10)
	v_fma_f32 v55, -v202, v52, v55
	v_fma_f32 v55, -v203, v53, v55
	v_fma_f32 v55, -v77, v204, v55
	v_fma_f32 v55, -v75, v205, v55
	ds_read_b128 v[202:205], v5 offset:33728
	s_waitcnt lgkmcnt(10)
	v_fma_f32 v56, -v48, v228, v75
	v_fma_f32 v56, -v49, v229, v56
	v_fma_f32 v56, -v230, v50, v56
	v_fma_f32 v56, -v231, v51, v56
	ds_read_b128 v[228:231], v5 offset:33744
	s_waitcnt lgkmcnt(10)
	v_fma_f32 v56, -v214, v52, v56
	v_fma_f32 v56, -v215, v53, v56
	v_fma_f32 v56, -v216, v55, v56
	v_fma_f32 v56, -v75, v217, v56
	ds_read_b128 v[214:217], v5 offset:33760
	s_waitcnt lgkmcnt(10)
	v_fma_f32 v58, -v48, v232, v76
	v_fma_f32 v58, -v49, v233, v58
	v_fma_f32 v58, -v50, v234, v58
	v_fma_f32 v58, -v235, v51, v58
	s_waitcnt lgkmcnt(9)
	v_fma_f32 v58, -v178, v52, v58
	v_fma_f32 v58, -v179, v53, v58
	v_fma_f32 v58, -v180, v55, v58
	v_fma_f32 v58, -v181, v56, v58
	ds_read_b128 v[178:181], v5 offset:33984
	s_waitcnt lgkmcnt(9)
	v_fma_f32 v61, -v48, v182, v74
	v_fma_f32 v61, -v49, v183, v61
	v_fma_f32 v61, -v50, v184, v61
	v_fma_f32 v61, -v185, v51, v61
	ds_read_b128 v[182:185], v5 offset:34000
	s_waitcnt lgkmcnt(9)
	v_fma_f32 v61, -v190, v52, v61
	v_fma_f32 v61, -v191, v53, v61
	v_fma_f32 v61, -v192, v55, v61
	v_fma_f32 v61, -v193, v56, v61
	ds_read_b128 v[190:193], v5 offset:34016
	s_waitcnt lgkmcnt(9)
	v_fma_f32 v61, -v186, v58, v61
	v_fma_f32 v61, -v74, v187, v61
	v_fma_f32 v61, -v73, v188, v61
	v_fma_f32 v61, -v72, v189, v61
	s_waitcnt lgkmcnt(8)
	v_fma_f32 v62, -v48, v198, v73
	v_fma_f32 v62, -v49, v199, v62
	v_fma_f32 v62, -v50, v200, v62
	v_fma_f32 v62, -v51, v201, v62
	ds_read_b128 v[198:201], v5 offset:34240
	s_waitcnt lgkmcnt(8)
	v_fma_f32 v62, -v52, v194, v62
	v_fma_f32 v62, -v195, v53, v62
	v_fma_f32 v62, -v196, v55, v62
	v_fma_f32 v62, -v197, v56, v62
	ds_read_b128 v[194:197], v5 offset:34256
	s_waitcnt lgkmcnt(8)
	v_fma_f32 v62, -v206, v58, v62
	v_fma_f32 v62, -v207, v61, v62
	v_fma_f32 v62, -v73, v208, v62
	v_fma_f32 v62, -v72, v209, v62
	ds_read_b128 v[206:209], v5 offset:34272
	s_waitcnt lgkmcnt(8)
	v_fma_f32 v63, -v48, v202, v72
	v_fma_f32 v63, -v49, v203, v63
	v_fma_f32 v63, -v50, v204, v63
	v_fma_f32 v63, -v51, v205, v63
	ds_read_b128 v[202:205], v5 offset:34288
	s_waitcnt lgkmcnt(8)
	v_fma_f32 v63, -v52, v228, v63
	v_fma_f32 v63, -v229, v53, v63
	v_fma_f32 v63, -v230, v55, v63
	v_fma_f32 v63, -v231, v56, v63
	ds_read_b128 v[228:231], v5 offset:34496
	s_waitcnt lgkmcnt(8)
	v_fma_f32 v63, -v214, v58, v63
	v_fma_f32 v63, -v215, v61, v63
	v_fma_f32 v63, -v216, v62, v63
	v_fma_f32 v63, -v72, v217, v63
	s_waitcnt lgkmcnt(7)
	v_fma_f32 v70, -v48, v178, v71
	v_fma_f32 v70, -v49, v179, v70
	v_fma_f32 v70, -v50, v180, v70
	v_fma_f32 v74, -v51, v181, v70
	ds_read_b128 v[178:181], v5 offset:34512
	s_waitcnt lgkmcnt(7)
	v_fma_f32 v70, -v52, v182, v74
	v_fma_f32 v70, -v53, v183, v70
	v_fma_f32 v70, -v184, v55, v70
	v_fma_f32 v74, -v185, v56, v70
	ds_read_b128 v[182:185], v5 offset:34528
	s_waitcnt lgkmcnt(7)
	v_fma_f32 v70, -v190, v58, v74
	v_fma_f32 v70, -v191, v61, v70
	v_fma_f32 v70, -v192, v62, v70
	v_fma_f32 v70, -v193, v63, v70
	ds_read_b128 v[190:193], v5 offset:34544
	s_waitcnt lgkmcnt(7)
	v_fma_f32 v71, -v48, v198, v59
	v_fma_f32 v71, -v49, v199, v71
	v_fma_f32 v71, -v50, v200, v71
	v_fma_f32 v71, -v51, v201, v71
	ds_read_b128 v[198:201], v5 offset:34752
	s_waitcnt lgkmcnt(7)
	v_fma_f32 v71, -v52, v194, v71
	v_fma_f32 v71, -v53, v195, v71
	v_fma_f32 v71, -v55, v196, v71
	v_fma_f32 v71, -v197, v56, v71
	ds_read_b128 v[194:197], v5 offset:34768
	s_waitcnt lgkmcnt(7)
	v_fma_f32 v71, -v206, v58, v71
	v_fma_f32 v71, -v207, v61, v71
	v_fma_f32 v71, -v208, v62, v71
	v_fma_f32 v71, -v209, v63, v71
	ds_read_b128 v[206:209], v5 offset:34784
	s_waitcnt lgkmcnt(7)
	v_fma_f32 v71, -v202, v70, v71
	v_fma_f32 v59, -v59, v203, v71
	v_fma_f32 v59, -v57, v204, v59
	v_fma_f32 v59, -v54, v205, v59
	ds_read_b128 v[202:205], v5 offset:34800
	s_waitcnt lgkmcnt(7)
	v_fma_f32 v71, -v48, v228, v57
	v_fma_f32 v71, -v49, v229, v71
	v_fma_f32 v71, -v50, v230, v71
	v_fma_f32 v71, -v51, v231, v71
	s_waitcnt lgkmcnt(6)
	v_fma_f32 v71, -v52, v178, v71
	v_fma_f32 v71, -v53, v179, v71
	v_fma_f32 v71, -v55, v180, v71
	v_fma_f32 v71, -v56, v181, v71
	s_waitcnt lgkmcnt(5)
	v_fma_f32 v71, -v58, v182, v71
	v_fma_f32 v71, -v183, v61, v71
	v_fma_f32 v71, -v184, v62, v71
	v_fma_f32 v71, -v185, v63, v71
	s_waitcnt lgkmcnt(4)
	v_fma_f32 v71, -v190, v70, v71
	v_fma_f32 v71, -v191, v59, v71
	v_fma_f32 v57, -v57, v192, v71
	v_fma_f32 v57, -v54, v193, v57
	s_waitcnt lgkmcnt(3)
	v_fma_f32 v71, -v48, v198, v54
	v_fma_f32 v71, -v49, v199, v71
	v_fma_f32 v71, -v50, v200, v71
	v_fma_f32 v71, -v51, v201, v71
	s_waitcnt lgkmcnt(2)
	v_fma_f32 v71, -v52, v194, v71
	v_fma_f32 v71, -v53, v195, v71
	v_fma_f32 v71, -v55, v196, v71
	v_fma_f32 v71, -v56, v197, v71
	s_waitcnt lgkmcnt(1)
	v_fma_f32 v71, -v58, v206, v71
	v_fma_f32 v71, -v61, v207, v71
	v_fma_f32 v71, -v208, v62, v71
	v_fma_f32 v71, -v209, v63, v71
	s_waitcnt lgkmcnt(0)
	v_fma_f32 v5, -v202, v70, v71
	v_fma_f32 v5, -v203, v59, v5
	v_fma_f32 v5, -v204, v57, v5
	v_fma_f32 v5, -v54, v205, v5
	v_mov_b32_e32 v72, v202
	v_mov_b32_e32 v73, v203
	v_mov_b32_e32 v74, v204
	v_mov_b32_e32 v75, v205
	v_mov_b32_e32 v76, v216
	v_mov_b32_e32 v77, v217
	v_mov_b32_e32 v78, v188
	v_mov_b32_e32 v79, v189
	v_mov_b32_e32 v80, v234
	v_mov_b32_e32 v81, v235
	v_mov_b32_e32 v82, v244
	v_mov_b32_e32 v83, v245
	v_mov_b32_e32 v84, v246
	v_mov_b32_e32 v85, v247
	v_mov_b32_e32 v86, v146
	v_mov_b32_e32 v87, v147
	v_mov_b32_e32 v88, v148
	v_mov_b32_e32 v89, v149
	v_mov_b32_e32 v90, v150
	v_mov_b32_e32 v91, v151
	v_mov_b32_e32 v92, v152
	v_mov_b32_e32 v93, v153
	v_readlane_b32 s16, v253, 32
	v_readlane_b32 s17, v253, 33
	s_mov_b64 s[12:13], -1
	s_and_b64 vcc, exec, s[16:17]
	s_cbranch_vccz .LBB0_811
	s_movk_i32 s6, 0x5000
	v_add_co_u32_e32 v68, vcc, s6, v68
	s_nop 1
	v_addc_co_u32_e32 v69, vcc, 0, v69, vcc
	v_cvt_pk_bf16_f32 v54, -v48, s0
	global_store_short v[68:69], v54, off offset:2048
	v_cvt_pk_bf16_f32 v54, -v49, s0
	global_store_short v[68:69], v54, off offset:2176
	v_cvt_pk_bf16_f32 v54, -v50, s0
	global_store_short v[68:69], v54, off offset:2304
	v_cvt_pk_bf16_f32 v54, -v51, s0
	global_store_short v[68:69], v54, off offset:2432
	v_cvt_pk_bf16_f32 v54, -v52, s0
	global_store_short v[68:69], v54, off offset:2560
	v_cvt_pk_bf16_f32 v54, -v53, s0
	global_store_short v[68:69], v54, off offset:2688
	v_cvt_pk_bf16_f32 v54, -v55, s0
	global_store_short v[68:69], v54, off offset:2816
	v_cvt_pk_bf16_f32 v54, -v56, s0
	global_store_short v[68:69], v54, off offset:2944
	v_cvt_pk_bf16_f32 v54, -v58, s0
	global_store_short v[68:69], v54, off offset:3072
	v_cvt_pk_bf16_f32 v54, -v61, s0
	global_store_short v[68:69], v54, off offset:3200
	v_cvt_pk_bf16_f32 v54, -v62, s0
	global_store_short v[68:69], v54, off offset:3328
	v_cvt_pk_bf16_f32 v54, -v63, s0
	global_store_short v[68:69], v54, off offset:3456
	v_cvt_pk_bf16_f32 v54, -v70, s0
	global_store_short v[68:69], v54, off offset:3584
	v_cvt_pk_bf16_f32 v54, -v59, s0
	global_store_short v[68:69], v54, off offset:3712
	v_cvt_pk_bf16_f32 v54, -v57, s0
	global_store_short v[68:69], v54, off offset:3840
	v_cvt_pk_bf16_f32 v54, -v5, s0
	global_store_short v[68:69], v54, off offset:3968
	s_mov_b64 s[12:13], 0
.LBB0_811:
	s_andn2_b64 vcc, exec, s[12:13]
	s_cbranch_vccnz .LBB0_162
	v_lshl_add_u64 v[66:67], v[66:67], 2, s[2:3]
	s_movk_i32 s2, 0x3000
	v_add_co_u32_e32 v0, vcc, s2, v66
	s_nop 1
	v_addc_co_u32_e32 v1, vcc, 0, v67, vcc
	global_store_dword v[0:1], v48, off
	global_store_dword v[0:1], v49, off offset:256
	global_store_dword v[0:1], v50, off offset:512
	global_store_dword v[0:1], v51, off offset:768
	global_store_dword v[0:1], v52, off offset:1024
	global_store_dword v[0:1], v53, off offset:1280
	global_store_dword v[0:1], v55, off offset:1536
	global_store_dword v[0:1], v56, off offset:1792
	global_store_dword v[0:1], v58, off offset:2048
	global_store_dword v[0:1], v61, off offset:2304
	global_store_dword v[0:1], v62, off offset:2560
	global_store_dword v[0:1], v63, off offset:2816
	global_store_dword v[0:1], v70, off offset:3072
	global_store_dword v[0:1], v59, off offset:3328
	global_store_dword v[0:1], v57, off offset:3584
	global_store_dword v[0:1], v5, off offset:3840
	s_branch .LBB0_162

	.amdhsa_kernel _Z9hymba_fwd2KP
		.amdhsa_group_segment_fixed_size 0
		.amdhsa_private_segment_fixed_size 0
		.amdhsa_kernarg_size 536
		.amdhsa_user_sgpr_count 2
		.amdhsa_user_sgpr_dispatch_ptr 0
		.amdhsa_user_sgpr_queue_ptr 0
		.amdhsa_user_sgpr_kernarg_segment_ptr 1
		.amdhsa_user_sgpr_dispatch_id 0
		.amdhsa_user_sgpr_kernarg_preload_length 0
		.amdhsa_user_sgpr_kernarg_preload_offset 0
		.amdhsa_user_sgpr_private_segment_size 0
		.amdhsa_uses_dynamic_stack 0
		.amdhsa_enable_private_segment 0
		.amdhsa_system_sgpr_workgroup_id_x 1
		.amdhsa_system_sgpr_workgroup_id_y 0
		.amdhsa_system_sgpr_workgroup_id_z 0
		.amdhsa_system_sgpr_workgroup_info 0
		.amdhsa_system_vgpr_workitem_id 2
		.amdhsa_next_free_vgpr 256
		.amdhsa_next_free_sgpr 102
		.amdhsa_accum_offset 256
		.amdhsa_reserve_vcc 1
		.amdhsa_float_round_mode_32 0
		.amdhsa_float_round_mode_16_64 0
		.amdhsa_float_denorm_mode_32 3
		.amdhsa_float_denorm_mode_16_64 3
		.amdhsa_dx10_clamp 1
		.amdhsa_ieee_mode 1
		.amdhsa_fp16_overflow 0
		.amdhsa_tg_split 0
		.amdhsa_exception_fp_ieee_invalid_op 0
		.amdhsa_exception_fp_denorm_src 0
		.amdhsa_exception_fp_ieee_div_zero 0
		.amdhsa_exception_fp_ieee_overflow 0
		.amdhsa_exception_fp_ieee_underflow 0
		.amdhsa_exception_fp_ieee_inexact 0
		.amdhsa_exception_int_div_zero 0
	.end_amdhsa_kernel

amdhsa.kernels:
  - .agpr_count:     0
    .args:
      - .offset:         0
        .size:           280
        .value_kind:     by_value
      - .offset:         280
        .size:           4
        .value_kind:     hidden_block_count_x
      - .offset:         284
        .size:           4
        .value_kind:     hidden_block_count_y
      - .offset:         288
        .size:           4
        .value_kind:     hidden_block_count_z
      - .offset:         292
        .size:           2
        .value_kind:     hidden_group_size_x
      - .offset:         294
        .size:           2
        .value_kind:     hidden_group_size_y
      - .offset:         296
        .size:           2
        .value_kind:     hidden_group_size_z
      - .offset:         298
        .size:           2
        .value_kind:     hidden_remainder_x
      - .offset:         300
        .size:           2
        .value_kind:     hidden_remainder_y
      - .offset:         302
        .size:           2
        .value_kind:     hidden_remainder_z
      - .offset:         320
        .size:           8
        .value_kind:     hidden_global_offset_x
      - .offset:         328
        .size:           8
        .value_kind:     hidden_global_offset_y
      - .offset:         336
        .size:           8
        .value_kind:     hidden_global_offset_z
      - .offset:         344
        .size:           2
        .value_kind:     hidden_grid_dims
      - .offset:         368
        .size:           8
        .value_kind:     hidden_multigrid_sync_arg
      - .offset:         400
        .size:           4
        .value_kind:     hidden_dynamic_lds_size
    .group_segment_fixed_size: 0
    .kernarg_segment_align: 8
    .kernarg_segment_size: 536
    .language:       OpenCL C
    .language_version:
      - 2
      - 0
    .max_flat_workgroup_size: 512
    .name:           _Z9hymba_fwd2KP
    .private_segment_fixed_size: 0
    .sgpr_count:     108
    .sgpr_spill_count: 282
    .symbol:         _Z9hymba_fwd2KP.kd
    .uniform_work_group_size: 1
    .uses_dynamic_stack: false
    .vgpr_count:     256
    .vgpr_spill_count: 0
    .wavefront_size: 64
